# attention compressed branch: K_cmp staged once per unit in LDS (cooperative load) instead of 8x redundant per-wave global fragment loads
# speedup vs baseline: 1.0642x; 1.0028x over previous
.LBB0_48:
	v_readlane_b32 s0, v252, 57
	s_bfe_u32 s4, s0, 0x70001
	s_bfe_u32 s0, s0, 0x20001
	v_lshl_add_u32 v2, s0, 9, v172
	v_readlane_b32 s2, v252, 62
	v_ashrrev_i32_e32 v3, 31, v2
	v_readlane_b32 s3, v252, 63
	s_waitcnt vmcnt(2)
	v_and_b32_e32 v47, 0xffff0000, v103
	v_writelane_b32 v253, s0, 0
	v_lshl_add_u64 v[2:3], v[2:3], 2, s[2:3]
	global_load_dword v1, v[2:3], off
	v_readlane_b32 s100, v252, 57
	s_bfe_u32 s100, s100, 0x70001
	s_lshl_b32 s100, s100, 14
	s_add_u32 s100, s100, 0x5000000
	v_readlane_b32 s101, v252, 62
	s_add_u32 s100, s100, s101
	v_readlane_b32 s101, v252, 63
	s_addc_u32 s101, s101, 0
	v_lshlrev_b32_e32 v6, 5, v172
	global_load_dwordx4 v[8:11], v6, s[100:101]
	global_load_dwordx4 v[12:15], v6, s[100:101] offset:16
	v_readlane_b32 s0, v252, 58
	v_readlane_b32 s1, v252, 59
	v_and_b32_e32 v2, 64, v209
	s_load_dwordx2 s[0:1], s[0:1], 0xf0
	v_add_u32_e32 v195, 64, v2
	v_lshlrev_b32_e32 v46, 16, v103
	v_mul_f32_e32 v50, v47, v47
	v_pk_fma_f32 v[58:59], v[46:47], v[46:47], v[50:51] op_sel_hi:[1,1,0]
	v_and_b32_e32 v51, 0xffff0000, v102
	v_lshlrev_b32_e32 v50, 16, v102
	v_mul_f32_e32 v54, v51, v51
	v_pk_fma_f32 v[60:61], v[50:51], v[50:51], v[54:55] op_sel_hi:[1,1,0]
	v_and_b32_e32 v55, 0xffff0000, v101
	v_and_b32_e32 v57, 0xffff0000, v100
	v_lshlrev_b32_e32 v54, 16, v101
	v_lshlrev_b32_e32 v56, 16, v100
	v_mov_b32_e32 v64, v55
	v_mov_b32_e32 v65, v57
	v_mov_b32_e32 v62, v54
	v_mov_b32_e32 v63, v56
	v_pk_mul_f32 v[64:65], v[64:65], v[64:65]
	v_and_b32_e32 v77, 0xffff0000, v106
	v_pk_fma_f32 v[66:67], v[62:63], v[62:63], v[64:65]
	v_and_b32_e32 v63, 0xffff0000, v99
	v_and_b32_e32 v65, 0xffff0000, v98
	v_lshlrev_b32_e32 v62, 16, v99
	v_lshlrev_b32_e32 v64, 16, v98
	v_mov_b32_e32 v70, v65
	v_mov_b32_e32 v71, v63
	v_mov_b32_e32 v68, v64
	v_mov_b32_e32 v69, v62
	v_pk_mul_f32 v[70:71], v[70:71], v[70:71]
	v_lshlrev_b32_e32 v76, 16, v106
	v_pk_fma_f32 v[68:69], v[68:69], v[68:69], v[70:71]
	v_and_b32_e32 v71, 0xffff0000, v108
	v_pk_add_f32 v[68:69], v[68:69], v[68:69] op_sel:[0,1] op_sel_hi:[1,0]
	v_lshlrev_b32_e32 v70, 16, v108
	v_pk_add_f32 v[68:69], v[66:67], v[68:69] op_sel:[1,0] op_sel_hi:[0,1]
	v_pk_add_f32 v[66:67], v[66:67], v[68:69]
	v_and_b32_e32 v69, 0xffff0000, v109
	v_lshlrev_b32_e32 v68, 16, v109
	v_mov_b32_e32 v74, v69
	v_mov_b32_e32 v75, v71
	v_mov_b32_e32 v72, v68
	v_mov_b32_e32 v73, v70
	v_pk_mul_f32 v[74:75], v[74:75], v[74:75]
	v_mov_b32_e32 v80, v77
	v_pk_fma_f32 v[72:73], v[72:73], v[72:73], v[74:75]
	v_and_b32_e32 v75, 0xffff0000, v107
	v_lshlrev_b32_e32 v74, 16, v107
	v_mov_b32_e32 v81, v75
	v_mov_b32_e32 v78, v76
	v_mov_b32_e32 v79, v74
	v_pk_mul_f32 v[80:81], v[80:81], v[80:81]
	s_waitcnt vmcnt(4)
	v_and_b32_e32 v37, 0xffff0000, v112
	v_pk_fma_f32 v[78:79], v[78:79], v[78:79], v[80:81]
	v_and_b32_e32 v43, 0xffff0000, v105
	v_pk_add_f32 v[78:79], v[78:79], v[78:79] op_sel:[0,1] op_sel_hi:[1,0]
	v_lshlrev_b32_e32 v36, 16, v112
	v_lshlrev_b32_e32 v38, 16, v111
	v_and_b32_e32 v39, 0xffff0000, v111
	v_and_b32_e32 v41, 0xffff0000, v110
	v_lshlrev_b32_e32 v42, 16, v105
	v_and_b32_e32 v45, 0xffff0000, v104
	v_pk_add_f32 v[78:79], v[72:73], v[78:79] op_sel:[1,0] op_sel_hi:[0,1]
	v_mov_b32_e32 v80, v43
	v_mov_b32_e32 v81, v37
	v_pk_mul_f32 v[52:53], v[38:39], v[38:39]
	v_lshlrev_b32_e32 v40, 16, v110
	v_lshlrev_b32_e32 v44, 16, v104
	v_pk_add_f32 v[72:73], v[72:73], v[78:79]
	v_mov_b32_e32 v78, v42
	v_mov_b32_e32 v79, v36
	v_pk_mul_f32 v[80:81], v[80:81], v[80:81]
	v_mov_b32_e32 v82, v45
	v_mov_b32_e32 v83, v41
	v_lshlrev_b32_e32 v34, 16, v113
	v_and_b32_e32 v35, 0xffff0000, v113
	v_pk_fma_f32 v[78:79], v[78:79], v[78:79], v[80:81]
	s_waitcnt vmcnt(0)
	v_mul_f32_e32 v1, 0x3fb8aa3b, v1
	ds_write_b32 v169, v1
	v_lshrrev_b32_e32 v2, 7, v172
	v_lshlrev_b32_e32 v3, 2, v172
	v_lshl_add_u32 v3, v2, 9, v3
	v_bfe_u32 v4, v172, 6, 1
	v_readlane_b32 s100, v1, 63
	v_add_u32_e32 v5, 0x22200, v3
	ds_write_b32 v5, v1
	v_lshl_add_u32 v3, v4, 9, v3
	v_cmp_ne_u32_e32 vcc, 0, v4
	v_mov_b32_e32 v5, s100
	v_add_u32_e32 v3, 0x22100, v3
	v_cndmask_b32_e32 v5, v210, v5, vcc
	ds_write_b32 v3, v5
	v_add_u32_e32 v7, v223, v224
	ds_write_b128 v7, v[8:11] offset:36864
	ds_write_b128 v7, v[12:15] offset:36880
	v_xor_b32_e32 v1, 32, v209
	v_cmp_lt_i32_e32 vcc, v1, v195
	v_mov_b32_e32 v80, v44
	v_mov_b32_e32 v81, v40
	v_cndmask_b32_e32 v1, v209, v1, vcc
	v_lshlrev_b32_e32 v163, 2, v1
	v_lshlrev_b32_e32 v1, 2, v174
	s_waitcnt lgkmcnt(0)
	global_load_dwordx4 v[26:29], v1, s[0:1] offset:16
	global_load_dwordx4 v[30:33], v1, s[0:1]
	global_load_dwordx4 v[18:21], v1, s[0:1] offset:80
	global_load_dwordx4 v[22:25], v1, s[0:1] offset:64
	global_load_dwordx4 v[10:13], v1, s[0:1] offset:144
	global_load_dwordx4 v[14:17], v1, s[0:1] offset:128
	global_load_dwordx4 v[2:5], v1, s[0:1] offset:208
	global_load_dwordx4 v[6:9], v1, s[0:1] offset:192
	v_pk_mul_f32 v[82:83], v[82:83], v[82:83]
	v_mov_b32_e32 v61, v52
	v_mov_b32_e32 v59, v53
	v_pk_mul_f32 v[48:49], v[34:35], v[34:35]
	v_pk_fma_f32 v[80:81], v[80:81], v[80:81], v[82:83]
	v_pk_add_f32 v[52:53], v[60:61], v[58:59]
	v_mov_b32_e32 v73, v48
	v_pk_add_f32 v[52:53], v[80:81], v[52:53]
	v_mov_b32_e32 v67, v49
	v_pk_add_f32 v[52:53], v[78:79], v[52:53]
	v_pk_add_f32 v[48:49], v[72:73], v[66:67]
	s_mov_b32 s0, 0x800000
	v_pk_add_f32 v[48:49], v[48:49], v[52:53]
	s_lshl_b32 s5, s50, 6
	v_add_f32_e32 v1, v48, v49
	ds_bpermute_b32 v48, v163, v1
	v_lshlrev_b32_e32 v96, 1, v174
	v_mov_b32_e32 v187, v97
	s_waitcnt lgkmcnt(0)
	s_barrier
	v_add_f32_e32 v1, v1, v48
	v_fmamk_f32 v1, v1, 0x3c800000, v207
	v_cmp_gt_f32_e32 vcc, s0, v1
	v_mul_f32_e32 v48, 0x4b800000, v1
	s_lshl_b32 s0, s4, 14
	v_cndmask_b32_e32 v1, v1, v48, vcc
	v_rsq_f32_e32 v1, v1
	s_add_u32 s0, s2, s0
	s_addc_u32 s1, s3, 0
	v_mul_f32_e32 v48, 0x45800000, v1
	v_cndmask_b32_e32 v1, v1, v48, vcc
	v_mul_f32_e32 v48, 0x3e38aa3b, v1
	v_pk_mul_f32 v[52:53], v[48:49], v[76:77] op_sel_hi:[0,1]
	v_mul_f32_e32 v0, 0xbfb8aa3b, v164
	v_writelane_b32 v253, s4, 1
	s_waitcnt vmcnt(6)
	v_pk_mul_f32 v[30:31], v[30:31], v[52:53]
	s_nop 0
	v_cvt_pk_bf16_f32 v114, v30, v31
	v_pk_mul_f32 v[30:31], v[48:49], v[74:75] op_sel_hi:[0,1]
	v_pk_mul_f32 v[30:31], v[32:33], v[30:31]
	s_nop 0
	v_cvt_pk_bf16_f32 v115, v30, v31
	v_pk_mul_f32 v[30:31], v[48:49], v[70:71] op_sel_hi:[0,1]
	v_pk_mul_f32 v[26:27], v[26:27], v[30:31]
	s_nop 0
	v_cvt_pk_bf16_f32 v116, v26, v27
	v_pk_mul_f32 v[26:27], v[48:49], v[68:69] op_sel_hi:[0,1]
	v_pk_mul_f32 v[26:27], v[28:29], v[26:27]
	s_nop 0
	v_cvt_pk_bf16_f32 v117, v26, v27
	v_pk_mul_f32 v[26:27], v[48:49], v[64:65] op_sel_hi:[0,1]
	s_waitcnt vmcnt(4)
	v_pk_mul_f32 v[22:23], v[22:23], v[26:27]
	s_nop 0
	v_cvt_pk_bf16_f32 v118, v22, v23
	v_pk_mul_f32 v[22:23], v[48:49], v[62:63] op_sel_hi:[0,1]
	v_pk_mul_f32 v[22:23], v[24:25], v[22:23]
	s_nop 0
	v_cvt_pk_bf16_f32 v119, v22, v23
	v_pk_mul_f32 v[22:23], v[48:49], v[56:57] op_sel_hi:[0,1]
	v_pk_mul_f32 v[18:19], v[18:19], v[22:23]
	s_nop 0
	v_cvt_pk_bf16_f32 v120, v18, v19
	v_pk_mul_f32 v[18:19], v[48:49], v[54:55] op_sel_hi:[0,1]
	v_pk_mul_f32 v[18:19], v[20:21], v[18:19]
	s_nop 0
	v_cvt_pk_bf16_f32 v121, v18, v19
	v_pk_mul_f32 v[18:19], v[48:49], v[50:51] op_sel_hi:[0,1]
	s_waitcnt vmcnt(2)
	v_pk_mul_f32 v[14:15], v[14:15], v[18:19]
	s_nop 0
	v_cvt_pk_bf16_f32 v122, v14, v15
	v_pk_mul_f32 v[14:15], v[48:49], v[46:47] op_sel_hi:[0,1]
	v_pk_mul_f32 v[14:15], v[16:17], v[14:15]
	s_nop 0
	v_cvt_pk_bf16_f32 v123, v14, v15
	v_pk_mul_f32 v[14:15], v[48:49], v[44:45] op_sel_hi:[0,1]
	v_pk_mul_f32 v[10:11], v[10:11], v[14:15]
	s_nop 0
	v_cvt_pk_bf16_f32 v124, v10, v11
	v_pk_mul_f32 v[10:11], v[48:49], v[42:43] op_sel_hi:[0,1]
	v_pk_mul_f32 v[10:11], v[12:13], v[10:11]
	s_nop 0
	v_cvt_pk_bf16_f32 v125, v10, v11
	v_pk_mul_f32 v[10:11], v[48:49], v[40:41] op_sel_hi:[0,1]
	s_waitcnt vmcnt(0)
	v_pk_mul_f32 v[6:7], v[6:7], v[10:11]
	s_nop 0
	v_cvt_pk_bf16_f32 v126, v6, v7
	v_pk_mul_f32 v[6:7], v[48:49], v[38:39] op_sel_hi:[0,1]
	v_pk_mul_f32 v[6:7], v[8:9], v[6:7]
	s_nop 0
	v_cvt_pk_bf16_f32 v127, v6, v7
	v_pk_mul_f32 v[6:7], v[48:49], v[36:37] op_sel_hi:[0,1]
	v_pk_mul_f32 v[2:3], v[2:3], v[6:7]
	s_nop 0
	v_cvt_pk_bf16_f32 v128, v2, v3
	v_pk_mul_f32 v[2:3], v[48:49], v[34:35] op_sel_hi:[0,1]
	v_pk_mul_f32 v[2:3], v[4:5], v[2:3]
	s_nop 0
	v_cvt_pk_bf16_f32 v129, v2, v3
	v_add_u32_e32 v131, v227, v229
	ds_read_b128 v[64:67], v131 offset:41472
	ds_read_b128 v[16:19], v131 offset:36864
	ds_read_b128 v[68:71], v131 offset:41504
	ds_read_b128 v[20:23], v131 offset:36896
	ds_read_b128 v[72:75], v131 offset:41536
	ds_read_b128 v[24:27], v131 offset:36928
	ds_read_b128 v[76:79], v131 offset:41568
	ds_read_b128 v[28:31], v131 offset:36960
	v_mov_b32_e32 v1, v0
	v_mov_b32_e32 v2, v0
	v_mov_b32_e32 v3, v0
	v_mov_b32_e32 v4, v0
	v_mov_b32_e32 v5, v0
	v_mov_b32_e32 v6, v0
	v_mov_b32_e32 v7, v0
	v_mov_b32_e32 v8, v0
	v_mov_b32_e32 v9, v0
	v_mov_b32_e32 v10, v0
	v_mov_b32_e32 v11, v0
	v_mov_b32_e32 v12, v0
	v_mov_b32_e32 v13, v0
	v_mov_b32_e32 v14, v0
	v_mov_b32_e32 v15, v0
	s_waitcnt lgkmcnt(7)
	v_mfma_f32_32x32x16_bf16 v[32:47], v[64:67], v[114:117], v[0:15]
	s_waitcnt lgkmcnt(6)
	v_mfma_f32_32x32x16_bf16 v[48:63], v[16:19], v[114:117], v[0:15]
	s_waitcnt lgkmcnt(5)
	v_mfma_f32_32x32x16_bf16 v[32:47], v[68:71], v[118:121], v[32:47]
	s_waitcnt lgkmcnt(4)
	v_mfma_f32_32x32x16_bf16 v[48:63], v[20:23], v[118:121], v[48:63]
	s_waitcnt lgkmcnt(3)
	v_mfma_f32_32x32x16_bf16 v[32:47], v[72:75], v[122:125], v[32:47]
	s_waitcnt lgkmcnt(2)
	v_mfma_f32_32x32x16_bf16 v[48:63], v[24:27], v[122:125], v[48:63]
	s_waitcnt lgkmcnt(1)
	v_mfma_f32_32x32x16_bf16 v[32:47], v[76:79], v[126:129], v[32:47]
	s_waitcnt lgkmcnt(0)
	v_mfma_f32_32x32x16_bf16 v[48:63], v[28:31], v[126:129], v[48:63]
	ds_read_b128 v[64:67], v131 offset:46080
	ds_read_b128 v[80:83], v131 offset:50688
	ds_read_b128 v[68:71], v131 offset:46112
	ds_read_b128 v[84:87], v131 offset:50720
	ds_read_b128 v[72:75], v131 offset:46144
	ds_read_b128 v[88:91], v131 offset:50752
	ds_read_b128 v[76:79], v131 offset:46176
	ds_read_b128 v[92:95], v131 offset:50784
	s_waitcnt lgkmcnt(7)
	v_mfma_f32_32x32x16_bf16 v[16:31], v[64:67], v[114:117], v[0:15]
	v_or_b32_e32 v164, s5, v167
	v_sub_u32_e32 v66, v164, v175
	v_writelane_b32 v253, s5, 2
	s_waitcnt lgkmcnt(6)
	v_mfma_f32_32x32x16_bf16 v[0:15], v[80:83], v[114:117], v[0:15]
	s_waitcnt lgkmcnt(5)
	v_mfma_f32_32x32x16_bf16 v[16:31], v[68:71], v[118:121], v[16:31]
	s_waitcnt lgkmcnt(4)
	v_mfma_f32_32x32x16_bf16 v[0:15], v[84:87], v[118:121], v[0:15]
	s_waitcnt lgkmcnt(3)
	v_mfma_f32_32x32x16_bf16 v[16:31], v[72:75], v[122:125], v[16:31]
	s_waitcnt lgkmcnt(2)
	v_mfma_f32_32x32x16_bf16 v[0:15], v[88:91], v[122:125], v[0:15]
	s_waitcnt lgkmcnt(1)
	v_mfma_f32_32x32x16_bf16 v[16:31], v[76:79], v[126:129], v[16:31]
	s_waitcnt lgkmcnt(0)
	v_mfma_f32_32x32x16_bf16 v[0:15], v[92:95], v[126:129], v[0:15]
	v_add_u32_e32 v131, 0xffffffe1, v66
	v_min_u32_e32 v132, 0x7f, v131
	v_lshl_add_u32 v132, v132, 2, s33
	ds_read_b32 v132, v132
	v_ashrrev_i32_e32 v131, 31, v131
	v_add_u32_e32 v133, 0xffffffd1, v66
	v_min_u32_e32 v134, 0x7f, v133
	v_lshl_add_u32 v134, v134, 2, s33
	ds_read_b32 v134, v134
	v_ashrrev_i32_e32 v133, 31, v133
	v_add_u32_e32 v135, 0xffffffc1, v66
	v_min_u32_e32 v136, 0x7f, v135
	v_lshl_add_u32 v136, v136, 2, s33
	ds_read_b32 v136, v136
	v_ashrrev_i32_e32 v135, 31, v135
	v_add_u32_e32 v137, 0xffffffb1, v66
	v_min_u32_e32 v138, 0x7f, v137
	v_lshl_add_u32 v138, v138, 2, s33
	ds_read_b32 v138, v138
	v_ashrrev_i32_e32 v137, 31, v137
	v_add_u32_e32 v139, 0xffffff61, v66
	v_min_u32_e32 v140, 0x7f, v139
	v_lshl_add_u32 v140, v140, 2, s33
	ds_read_b32 v140, v140
	v_ashrrev_i32_e32 v139, 31, v139
	v_add_u32_e32 v141, 0xffffff51, v66
	v_min_u32_e32 v142, 0x7f, v141
	v_lshl_add_u32 v142, v142, 2, s33
	ds_read_b32 v142, v142
	v_ashrrev_i32_e32 v141, 31, v141
	v_add_u32_e32 v143, 0xffffff41, v66
	v_min_u32_e32 v144, 0x7f, v143
	v_lshl_add_u32 v144, v144, 2, s33
	ds_read_b32 v144, v144
	v_ashrrev_i32_e32 v143, 31, v143
	v_add_u32_e32 v145, 0xffffff31, v66
	v_min_u32_e32 v146, 0x7f, v145
	v_lshl_add_u32 v146, v146, 2, s33
	ds_read_b32 v146, v146
	v_ashrrev_i32_e32 v145, 31, v145
	v_add_u32_e32 v147, 0xfffffee1, v66
	v_min_u32_e32 v148, 0x7f, v147
	v_lshl_add_u32 v148, v148, 2, s33
	ds_read_b32 v148, v148
	v_ashrrev_i32_e32 v147, 31, v147
	v_add_u32_e32 v149, 0xfffffed1, v66
	v_min_u32_e32 v150, 0x7f, v149
	v_lshl_add_u32 v150, v150, 2, s33
	ds_read_b32 v150, v150
	v_ashrrev_i32_e32 v149, 31, v149
	v_add_u32_e32 v151, 0xfffffec1, v66
	v_min_u32_e32 v152, 0x7f, v151
	v_lshl_add_u32 v152, v152, 2, s33
	ds_read_b32 v152, v152
	v_ashrrev_i32_e32 v151, 31, v151
	v_add_u32_e32 v153, 0xfffffeb1, v66
	v_min_u32_e32 v154, 0x7f, v153
	v_lshl_add_u32 v154, v154, 2, s33
	ds_read_b32 v154, v154
	v_ashrrev_i32_e32 v153, 31, v153
	v_add_u32_e32 v155, 0xfffffe61, v66
	v_min_u32_e32 v156, 0x7f, v155
	v_lshl_add_u32 v156, v156, 2, s33
	ds_read_b32 v156, v156
	v_ashrrev_i32_e32 v155, 31, v155
	v_add_u32_e32 v157, 0xfffffe51, v66
	v_min_u32_e32 v158, 0x7f, v157
	v_lshl_add_u32 v158, v158, 2, s33
	ds_read_b32 v158, v158
	v_ashrrev_i32_e32 v157, 31, v157
	v_add_u32_e32 v159, 0xfffffe41, v66
	v_min_u32_e32 v160, 0x7f, v159
	v_lshl_add_u32 v160, v160, 2, s33
	ds_read_b32 v160, v160
	v_ashrrev_i32_e32 v159, 31, v159
	s_waitcnt lgkmcnt(14)
	v_add_f32_e32 v65, v48, v132
	v_exp_f32_e32 v65, v65
	s_nop 0
	v_bfi_b32 v65, v131, 0, v65
	v_add_u32_e32 v131, 0xfffffe31, v66
	v_min_u32_e32 v132, 0x7f, v131
	v_lshl_add_u32 v132, v132, 2, s33
	ds_read_b32 v132, v132
	v_ashrrev_i32_e32 v131, 31, v131
	s_waitcnt lgkmcnt(14)
	v_add_f32_e32 v64, v49, v134
	v_exp_f32_e32 v64, v64
	v_add_f32_e32 v161, 0, v65
	v_bfi_b32 v64, v133, 0, v64
	v_add_u32_e32 v133, 0xfffffde1, v66
	v_min_u32_e32 v134, 0x7f, v133
	v_lshl_add_u32 v134, v134, 2, s33
	ds_read_b32 v134, v134
	v_ashrrev_i32_e32 v133, 31, v133
	s_waitcnt lgkmcnt(14)
	v_add_f32_e32 v49, v50, v136
	v_exp_f32_e32 v49, v49
	v_add_f32_e32 v161, v161, v64
	v_bfi_b32 v49, v135, 0, v49
	v_add_u32_e32 v135, 0xfffffdd1, v66
	v_min_u32_e32 v136, 0x7f, v135
	v_lshl_add_u32 v136, v136, 2, s33
	ds_read_b32 v136, v136
	v_ashrrev_i32_e32 v135, 31, v135
	s_waitcnt lgkmcnt(14)
	v_add_f32_e32 v48, v51, v138
	v_exp_f32_e32 v48, v48
	v_add_f32_e32 v161, v161, v49
	v_bfi_b32 v48, v137, 0, v48
	v_add_u32_e32 v137, 0xfffffdc1, v66
	v_min_u32_e32 v138, 0x7f, v137
	v_lshl_add_u32 v138, v138, 2, s33
	ds_read_b32 v138, v138
	v_ashrrev_i32_e32 v137, 31, v137
	s_waitcnt lgkmcnt(14)
	v_add_f32_e32 v51, v52, v140
	v_exp_f32_e32 v51, v51
	v_add_f32_e32 v161, v161, v48
	v_bfi_b32 v51, v139, 0, v51
	v_add_u32_e32 v139, 0xfffffdb1, v66
	v_min_u32_e32 v140, 0x7f, v139
	v_lshl_add_u32 v140, v140, 2, s33
	ds_read_b32 v140, v140
	v_ashrrev_i32_e32 v139, 31, v139
	s_waitcnt lgkmcnt(14)
	v_add_f32_e32 v50, v53, v142
	v_exp_f32_e32 v50, v50
	v_add_f32_e32 v161, v161, v51
	v_bfi_b32 v50, v141, 0, v50
	v_add_u32_e32 v141, 0xfffffd61, v66
	v_min_u32_e32 v142, 0x7f, v141
	v_lshl_add_u32 v142, v142, 2, s33
	ds_read_b32 v142, v142
	v_ashrrev_i32_e32 v141, 31, v141
	s_waitcnt lgkmcnt(14)
	v_add_f32_e32 v53, v54, v144
	v_exp_f32_e32 v53, v53
	v_add_f32_e32 v161, v161, v50
	v_bfi_b32 v53, v143, 0, v53
	v_add_u32_e32 v143, 0xfffffd51, v66
	v_min_u32_e32 v144, 0x7f, v143
	v_lshl_add_u32 v144, v144, 2, s33
	ds_read_b32 v144, v144
	v_ashrrev_i32_e32 v143, 31, v143
	s_waitcnt lgkmcnt(14)
	v_add_f32_e32 v52, v55, v146
	v_exp_f32_e32 v52, v52
	v_add_f32_e32 v161, v161, v53
	v_bfi_b32 v52, v145, 0, v52
	v_add_u32_e32 v145, 0xfffffd41, v66
	v_min_u32_e32 v146, 0x7f, v145
	v_lshl_add_u32 v146, v146, 2, s33
	ds_read_b32 v146, v146
	v_ashrrev_i32_e32 v145, 31, v145
	s_waitcnt lgkmcnt(14)
	v_add_f32_e32 v55, v56, v148
	v_exp_f32_e32 v55, v55
	v_add_f32_e32 v161, v161, v52
	v_bfi_b32 v55, v147, 0, v55
	v_add_u32_e32 v147, 0xfffffd31, v66
	v_min_u32_e32 v148, 0x7f, v147
	v_lshl_add_u32 v148, v148, 2, s33
	ds_read_b32 v148, v148
	v_ashrrev_i32_e32 v147, 31, v147
	s_waitcnt lgkmcnt(14)
	v_add_f32_e32 v54, v57, v150
	v_exp_f32_e32 v54, v54
	v_add_f32_e32 v161, v161, v55
	v_bfi_b32 v54, v149, 0, v54
	v_add_u32_e32 v149, 0xfffffce1, v66
	v_min_u32_e32 v150, 0x7f, v149
	v_lshl_add_u32 v150, v150, 2, s33
	ds_read_b32 v150, v150
	v_ashrrev_i32_e32 v149, 31, v149
	s_waitcnt lgkmcnt(14)
	v_add_f32_e32 v57, v58, v152
	v_exp_f32_e32 v57, v57
	v_add_f32_e32 v161, v161, v54
	v_bfi_b32 v57, v151, 0, v57
	v_add_u32_e32 v151, 0xfffffcd1, v66
	v_min_u32_e32 v152, 0x7f, v151
	v_lshl_add_u32 v152, v152, 2, s33
	ds_read_b32 v152, v152
	v_ashrrev_i32_e32 v151, 31, v151
	s_waitcnt lgkmcnt(14)
	v_add_f32_e32 v56, v59, v154
	v_exp_f32_e32 v56, v56
	v_add_f32_e32 v161, v161, v57
	v_bfi_b32 v56, v153, 0, v56
	v_add_u32_e32 v153, 0xfffffcc1, v66
	v_min_u32_e32 v154, 0x7f, v153
	v_lshl_add_u32 v154, v154, 2, s33
	ds_read_b32 v154, v154
	v_ashrrev_i32_e32 v153, 31, v153
	s_waitcnt lgkmcnt(14)
	v_add_f32_e32 v59, v60, v156
	v_exp_f32_e32 v59, v59
	v_add_f32_e32 v161, v161, v56
	v_bfi_b32 v59, v155, 0, v59
	v_add_u32_e32 v155, 0xfffffcb1, v66
	v_min_u32_e32 v156, 0x7f, v155
	v_lshl_add_u32 v156, v156, 2, s33
	ds_read_b32 v156, v156
	v_ashrrev_i32_e32 v155, 31, v155
	s_waitcnt lgkmcnt(14)
	v_add_f32_e32 v58, v61, v158
	v_exp_f32_e32 v58, v58
	v_add_f32_e32 v161, v161, v59
	v_bfi_b32 v58, v157, 0, v58
	v_add_u32_e32 v157, 0xfffffc61, v66
	v_min_u32_e32 v158, 0x7f, v157
	v_lshl_add_u32 v158, v158, 2, s33
	ds_read_b32 v158, v158
	v_ashrrev_i32_e32 v157, 31, v157
	s_waitcnt lgkmcnt(14)
	v_add_f32_e32 v61, v62, v160
	v_exp_f32_e32 v61, v61
	v_add_f32_e32 v161, v161, v58
	v_bfi_b32 v61, v159, 0, v61
	v_add_u32_e32 v159, 0xfffffc51, v66
	v_min_u32_e32 v160, 0x7f, v159
	v_lshl_add_u32 v160, v160, 2, s33
	ds_read_b32 v160, v160
	v_ashrrev_i32_e32 v159, 31, v159
	s_waitcnt lgkmcnt(14)
	v_add_f32_e32 v60, v63, v132
	v_exp_f32_e32 v60, v60
	v_add_f32_e32 v161, v161, v61
	v_bfi_b32 v60, v131, 0, v60
	v_add_u32_e32 v131, 0xfffffc41, v66
	v_min_u32_e32 v132, 0x7f, v131
	v_lshl_add_u32 v132, v132, 2, s33
	ds_read_b32 v132, v132
	v_ashrrev_i32_e32 v131, 31, v131
	s_waitcnt lgkmcnt(14)
	v_add_f32_e32 v63, v32, v134
	v_exp_f32_e32 v63, v63
	v_add_f32_e32 v161, v161, v60
	v_bfi_b32 v63, v133, 0, v63
	v_add_u32_e32 v133, 0xfffffc31, v66
	v_min_u32_e32 v134, 0x7f, v133
	v_lshl_add_u32 v134, v134, 2, s33
	ds_read_b32 v134, v134
	v_ashrrev_i32_e32 v133, 31, v133
	s_waitcnt lgkmcnt(14)
	v_add_f32_e32 v62, v33, v136
	v_exp_f32_e32 v62, v62
	v_add_f32_e32 v161, v161, v63
	v_bfi_b32 v62, v135, 0, v62
	v_add_u32_e32 v135, 0xfffffbe1, v66
	v_min_u32_e32 v136, 0x7f, v135
	v_lshl_add_u32 v136, v136, 2, s33
	ds_read_b32 v136, v136
	v_ashrrev_i32_e32 v135, 31, v135
	s_waitcnt lgkmcnt(14)
	v_add_f32_e32 v33, v34, v138
	v_exp_f32_e32 v33, v33
	v_add_f32_e32 v161, v161, v62
	v_bfi_b32 v33, v137, 0, v33
	v_add_u32_e32 v137, 0xfffffbd1, v66
	v_min_u32_e32 v138, 0x7f, v137
	v_lshl_add_u32 v138, v138, 2, s33
	ds_read_b32 v138, v138
	v_ashrrev_i32_e32 v137, 31, v137
	s_waitcnt lgkmcnt(14)
	v_add_f32_e32 v32, v35, v140
	v_exp_f32_e32 v32, v32
	v_add_f32_e32 v161, v161, v33
	v_bfi_b32 v32, v139, 0, v32
	v_add_u32_e32 v139, 0xfffffbc1, v66
	v_min_u32_e32 v140, 0x7f, v139
	v_lshl_add_u32 v140, v140, 2, s33
	ds_read_b32 v140, v140
	v_ashrrev_i32_e32 v139, 31, v139
	s_waitcnt lgkmcnt(14)
	v_add_f32_e32 v35, v36, v142
	v_exp_f32_e32 v35, v35
	v_add_f32_e32 v161, v161, v32
	v_bfi_b32 v35, v141, 0, v35
	v_add_u32_e32 v141, 0xfffffbb1, v66
	v_min_u32_e32 v142, 0x7f, v141
	v_lshl_add_u32 v142, v142, 2, s33
	ds_read_b32 v142, v142
	v_ashrrev_i32_e32 v141, 31, v141
	s_waitcnt lgkmcnt(14)
	v_add_f32_e32 v34, v37, v144
	v_exp_f32_e32 v34, v34
	v_add_f32_e32 v161, v161, v35
	v_bfi_b32 v34, v143, 0, v34
	v_add_u32_e32 v143, 0xfffffb61, v66
	v_min_u32_e32 v144, 0x7f, v143
	v_lshl_add_u32 v144, v144, 2, s33
	ds_read_b32 v144, v144
	v_ashrrev_i32_e32 v143, 31, v143
	s_waitcnt lgkmcnt(14)
	v_add_f32_e32 v37, v38, v146
	v_exp_f32_e32 v37, v37
	v_add_f32_e32 v161, v161, v34
	v_bfi_b32 v37, v145, 0, v37
	v_add_u32_e32 v145, 0xfffffb51, v66
	v_min_u32_e32 v146, 0x7f, v145
	v_lshl_add_u32 v146, v146, 2, s33
	ds_read_b32 v146, v146
	v_ashrrev_i32_e32 v145, 31, v145
	s_waitcnt lgkmcnt(14)
	v_add_f32_e32 v36, v39, v148
	v_exp_f32_e32 v36, v36
	v_add_f32_e32 v161, v161, v37
	v_bfi_b32 v36, v147, 0, v36
	v_add_u32_e32 v147, 0xfffffb41, v66
	v_min_u32_e32 v148, 0x7f, v147
	v_lshl_add_u32 v148, v148, 2, s33
	ds_read_b32 v148, v148
	v_ashrrev_i32_e32 v147, 31, v147
	s_waitcnt lgkmcnt(14)
	v_add_f32_e32 v39, v40, v150
	v_exp_f32_e32 v39, v39
	v_add_f32_e32 v161, v161, v36
	v_bfi_b32 v39, v149, 0, v39
	v_add_u32_e32 v149, 0xfffffb31, v66
	v_min_u32_e32 v150, 0x7f, v149
	v_lshl_add_u32 v150, v150, 2, s33
	ds_read_b32 v150, v150
	v_ashrrev_i32_e32 v149, 31, v149
	s_waitcnt lgkmcnt(14)
	v_add_f32_e32 v38, v41, v152
	v_exp_f32_e32 v38, v38
	v_add_f32_e32 v161, v161, v39
	v_bfi_b32 v38, v151, 0, v38
	v_add_u32_e32 v151, 0xfffffae1, v66
	v_min_u32_e32 v152, 0x7f, v151
	v_lshl_add_u32 v152, v152, 2, s33
	ds_read_b32 v152, v152
	v_ashrrev_i32_e32 v151, 31, v151
	s_waitcnt lgkmcnt(14)
	v_add_f32_e32 v41, v42, v154
	v_exp_f32_e32 v41, v41
	v_add_f32_e32 v161, v161, v38
	v_bfi_b32 v41, v153, 0, v41
	v_add_u32_e32 v153, 0xfffffad1, v66
	v_min_u32_e32 v154, 0x7f, v153
	v_lshl_add_u32 v154, v154, 2, s33
	ds_read_b32 v154, v154
	v_ashrrev_i32_e32 v153, 31, v153
	s_waitcnt lgkmcnt(14)
	v_add_f32_e32 v40, v43, v156
	v_exp_f32_e32 v40, v40
	v_add_f32_e32 v161, v161, v41
	v_bfi_b32 v40, v155, 0, v40
	v_add_u32_e32 v155, 0xfffffac1, v66
	v_min_u32_e32 v156, 0x7f, v155
	v_lshl_add_u32 v156, v156, 2, s33
	ds_read_b32 v156, v156
	v_ashrrev_i32_e32 v155, 31, v155
	s_waitcnt lgkmcnt(14)
	v_add_f32_e32 v67, v44, v158
	v_exp_f32_e32 v67, v67
	v_add_f32_e32 v161, v161, v40
	v_bfi_b32 v67, v157, 0, v67
	v_add_u32_e32 v157, 0xfffffab1, v66
	v_min_u32_e32 v158, 0x7f, v157
	v_lshl_add_u32 v158, v158, 2, s33
	ds_read_b32 v158, v158
	v_ashrrev_i32_e32 v157, 31, v157
	s_waitcnt lgkmcnt(14)
	v_add_f32_e32 v43, v45, v160
	v_exp_f32_e32 v43, v43
	v_add_f32_e32 v161, v161, v67
	v_bfi_b32 v43, v159, 0, v43
	v_add_u32_e32 v159, 0xfffffa61, v66
	v_min_u32_e32 v160, 0x7f, v159
	v_lshl_add_u32 v160, v160, 2, s33
	ds_read_b32 v160, v160
	v_ashrrev_i32_e32 v159, 31, v159
	s_waitcnt lgkmcnt(14)
	v_add_f32_e32 v69, v46, v132
	v_exp_f32_e32 v69, v69
	v_add_f32_e32 v161, v161, v43
	v_bfi_b32 v69, v131, 0, v69
	v_add_u32_e32 v131, 0xfffffa51, v66
	v_min_u32_e32 v132, 0x7f, v131
	v_lshl_add_u32 v132, v132, 2, s33
	ds_read_b32 v132, v132
	v_ashrrev_i32_e32 v131, 31, v131
	s_waitcnt lgkmcnt(14)
	v_add_f32_e32 v68, v47, v134
	v_exp_f32_e32 v68, v68
	v_add_f32_e32 v161, v161, v69
	v_bfi_b32 v68, v133, 0, v68
	v_add_u32_e32 v133, 0xfffffa41, v66
	v_min_u32_e32 v134, 0x7f, v133
	v_lshl_add_u32 v134, v134, 2, s33
	ds_read_b32 v134, v134
	v_ashrrev_i32_e32 v133, 31, v133
	s_waitcnt lgkmcnt(14)
	v_add_f32_e32 v44, v16, v136
	v_exp_f32_e32 v44, v44
	v_add_f32_e32 v161, v161, v68
	v_bfi_b32 v44, v135, 0, v44
	v_add_u32_e32 v135, 0xfffffa31, v66
	v_min_u32_e32 v136, 0x7f, v135
	v_lshl_add_u32 v136, v136, 2, s33
	ds_read_b32 v136, v136
	v_ashrrev_i32_e32 v135, 31, v135
	s_waitcnt lgkmcnt(14)
	v_add_f32_e32 v42, v17, v138
	v_exp_f32_e32 v42, v42
	v_add_f32_e32 v161, v161, v44
	v_bfi_b32 v42, v137, 0, v42
	v_add_u32_e32 v137, 0xfffff9e1, v66
	v_min_u32_e32 v138, 0x7f, v137
	v_lshl_add_u32 v138, v138, 2, s33
	ds_read_b32 v138, v138
	v_ashrrev_i32_e32 v137, 31, v137
	s_waitcnt lgkmcnt(14)
	v_add_f32_e32 v46, v18, v140
	v_exp_f32_e32 v46, v46
	v_add_f32_e32 v161, v161, v42
	v_bfi_b32 v46, v139, 0, v46
	v_add_u32_e32 v139, 0xfffff9d1, v66
	v_min_u32_e32 v140, 0x7f, v139
	v_lshl_add_u32 v140, v140, 2, s33
	ds_read_b32 v140, v140
	v_ashrrev_i32_e32 v139, 31, v139
	s_waitcnt lgkmcnt(14)
	v_add_f32_e32 v45, v19, v142
	v_exp_f32_e32 v45, v45
	v_add_f32_e32 v161, v161, v46
	v_bfi_b32 v45, v141, 0, v45
	v_add_u32_e32 v141, 0xfffff9c1, v66
	v_min_u32_e32 v142, 0x7f, v141
	v_lshl_add_u32 v142, v142, 2, s33
	ds_read_b32 v142, v142
	v_ashrrev_i32_e32 v141, 31, v141
	s_waitcnt lgkmcnt(14)
	v_add_f32_e32 v70, v20, v144
	v_exp_f32_e32 v70, v70
	v_add_f32_e32 v161, v161, v45
	v_bfi_b32 v70, v143, 0, v70
	v_add_u32_e32 v143, 0xfffff9b1, v66
	v_min_u32_e32 v144, 0x7f, v143
	v_lshl_add_u32 v144, v144, 2, s33
	ds_read_b32 v144, v144
	v_ashrrev_i32_e32 v143, 31, v143
	s_waitcnt lgkmcnt(14)
	v_add_f32_e32 v47, v21, v146
	v_exp_f32_e32 v47, v47
	v_add_f32_e32 v161, v161, v70
	v_bfi_b32 v47, v145, 0, v47
	v_add_u32_e32 v145, 0xfffff961, v66
	v_min_u32_e32 v146, 0x7f, v145
	v_lshl_add_u32 v146, v146, 2, s33
	ds_read_b32 v146, v146
	v_ashrrev_i32_e32 v145, 31, v145
	s_waitcnt lgkmcnt(14)
	v_add_f32_e32 v72, v22, v148
	v_exp_f32_e32 v72, v72
	v_add_f32_e32 v161, v161, v47
	v_bfi_b32 v72, v147, 0, v72
	v_add_u32_e32 v147, 0xfffff951, v66
	v_min_u32_e32 v148, 0x7f, v147
	v_lshl_add_u32 v148, v148, 2, s33
	ds_read_b32 v148, v148
	v_ashrrev_i32_e32 v147, 31, v147
	s_waitcnt lgkmcnt(14)
	v_add_f32_e32 v71, v23, v150
	v_exp_f32_e32 v71, v71
	v_add_f32_e32 v161, v161, v72
	v_bfi_b32 v71, v149, 0, v71
	v_add_u32_e32 v149, 0xfffff941, v66
	v_min_u32_e32 v150, 0x7f, v149
	v_lshl_add_u32 v150, v150, 2, s33
	ds_read_b32 v150, v150
	v_ashrrev_i32_e32 v149, 31, v149
	s_waitcnt lgkmcnt(14)
	v_add_f32_e32 v74, v24, v152
	v_exp_f32_e32 v74, v74
	v_add_f32_e32 v161, v161, v71
	v_bfi_b32 v74, v151, 0, v74
	v_add_u32_e32 v151, 0xfffff931, v66
	v_min_u32_e32 v152, 0x7f, v151
	v_lshl_add_u32 v152, v152, 2, s33
	ds_read_b32 v152, v152
	v_ashrrev_i32_e32 v151, 31, v151
	s_waitcnt lgkmcnt(14)
	v_add_f32_e32 v73, v25, v154
	v_exp_f32_e32 v73, v73
	v_add_f32_e32 v161, v161, v74
	v_bfi_b32 v73, v153, 0, v73
	v_add_u32_e32 v153, 0xfffff8e1, v66
	v_min_u32_e32 v154, 0x7f, v153
	v_lshl_add_u32 v154, v154, 2, s33
	ds_read_b32 v154, v154
	v_ashrrev_i32_e32 v153, 31, v153
	s_waitcnt lgkmcnt(14)
	v_add_f32_e32 v76, v26, v156
	v_exp_f32_e32 v76, v76
	v_add_f32_e32 v161, v161, v73
	v_bfi_b32 v76, v155, 0, v76
	v_add_u32_e32 v155, 0xfffff8d1, v66
	v_min_u32_e32 v156, 0x7f, v155
	v_lshl_add_u32 v156, v156, 2, s33
	ds_read_b32 v156, v156
	v_ashrrev_i32_e32 v155, 31, v155
	s_waitcnt lgkmcnt(14)
	v_add_f32_e32 v75, v27, v158
	v_exp_f32_e32 v75, v75
	v_add_f32_e32 v161, v161, v76
	v_bfi_b32 v75, v157, 0, v75
	v_add_u32_e32 v157, 0xfffff8c1, v66
	v_min_u32_e32 v158, 0x7f, v157
	v_lshl_add_u32 v158, v158, 2, s33
	ds_read_b32 v158, v158
	v_ashrrev_i32_e32 v157, 31, v157
	s_waitcnt lgkmcnt(14)
	v_add_f32_e32 v78, v28, v160
	v_exp_f32_e32 v78, v78
	v_add_f32_e32 v161, v161, v75
	v_bfi_b32 v78, v159, 0, v78
	v_add_u32_e32 v159, 0xfffff8b1, v66
	v_min_u32_e32 v160, 0x7f, v159
	v_lshl_add_u32 v160, v160, 2, s33
	ds_read_b32 v160, v160
	v_ashrrev_i32_e32 v159, 31, v159
	s_waitcnt lgkmcnt(14)
	v_add_f32_e32 v77, v29, v132
	v_exp_f32_e32 v77, v77
	v_add_f32_e32 v161, v161, v78
	v_bfi_b32 v77, v131, 0, v77
	v_add_u32_e32 v131, 0xfffff861, v66
	v_min_u32_e32 v132, 0x7f, v131
	v_lshl_add_u32 v132, v132, 2, s33
	ds_read_b32 v132, v132
	v_ashrrev_i32_e32 v131, 31, v131
	s_waitcnt lgkmcnt(14)
	v_add_f32_e32 v80, v30, v134
	v_exp_f32_e32 v80, v80
	v_add_f32_e32 v161, v161, v77
	v_bfi_b32 v80, v133, 0, v80
	v_add_u32_e32 v133, 0xfffff851, v66
	v_min_u32_e32 v134, 0x7f, v133
	v_lshl_add_u32 v134, v134, 2, s33
	ds_read_b32 v134, v134
	v_ashrrev_i32_e32 v133, 31, v133
	s_waitcnt lgkmcnt(14)
	v_add_f32_e32 v79, v31, v136
	v_exp_f32_e32 v79, v79
	v_add_f32_e32 v161, v161, v80
	v_bfi_b32 v79, v135, 0, v79
	v_add_u32_e32 v135, 0xfffff841, v66
	v_min_u32_e32 v136, 0x7f, v135
	v_lshl_add_u32 v136, v136, 2, s33
	ds_read_b32 v136, v136
	v_ashrrev_i32_e32 v135, 31, v135
	s_waitcnt lgkmcnt(14)
	v_add_f32_e32 v82, v0, v138
	v_exp_f32_e32 v82, v82
	v_add_f32_e32 v161, v161, v79
	v_bfi_b32 v82, v137, 0, v82
	v_add_u32_e32 v137, 0xfffff831, v66
	v_min_u32_e32 v138, 0x7f, v137
	v_lshl_add_u32 v138, v138, 2, s33
	ds_read_b32 v138, v138
	v_ashrrev_i32_e32 v137, 31, v137
	s_waitcnt lgkmcnt(14)
	v_add_f32_e32 v81, v1, v140
	v_exp_f32_e32 v81, v81
	v_add_f32_e32 v161, v161, v82
	v_bfi_b32 v81, v139, 0, v81
	s_waitcnt lgkmcnt(13)
	v_add_f32_e32 v84, v2, v142
	v_exp_f32_e32 v84, v84
	v_add_f32_e32 v161, v161, v81
	v_bfi_b32 v84, v141, 0, v84
	s_waitcnt lgkmcnt(12)
	v_add_f32_e32 v83, v3, v144
	v_exp_f32_e32 v83, v83
	v_add_f32_e32 v161, v161, v84
	v_bfi_b32 v83, v143, 0, v83
	s_waitcnt lgkmcnt(11)
	v_add_f32_e32 v86, v4, v146
	v_exp_f32_e32 v86, v86
	v_add_f32_e32 v161, v161, v83
	v_bfi_b32 v86, v145, 0, v86
	s_waitcnt lgkmcnt(10)
	v_add_f32_e32 v85, v5, v148
	v_exp_f32_e32 v85, v85
	v_add_f32_e32 v161, v161, v86
	v_bfi_b32 v85, v147, 0, v85
	s_waitcnt lgkmcnt(9)
	v_add_f32_e32 v88, v6, v150
	v_exp_f32_e32 v88, v88
	v_add_f32_e32 v161, v161, v85
	v_bfi_b32 v88, v149, 0, v88
	s_waitcnt lgkmcnt(8)
	v_add_f32_e32 v87, v7, v152
	v_exp_f32_e32 v87, v87
	v_add_f32_e32 v161, v161, v88
	v_bfi_b32 v87, v151, 0, v87
	s_waitcnt lgkmcnt(7)
	v_add_f32_e32 v90, v8, v154
	v_exp_f32_e32 v90, v90
	v_add_f32_e32 v161, v161, v87
	v_bfi_b32 v90, v153, 0, v90
	s_waitcnt lgkmcnt(6)
	v_add_f32_e32 v89, v9, v156
	v_exp_f32_e32 v89, v89
	v_add_f32_e32 v161, v161, v90
	v_bfi_b32 v89, v155, 0, v89
	s_waitcnt lgkmcnt(5)
	v_add_f32_e32 v92, v10, v158
	v_exp_f32_e32 v92, v92
	v_add_f32_e32 v161, v161, v89
	v_bfi_b32 v92, v157, 0, v92
	s_waitcnt lgkmcnt(4)
	v_add_f32_e32 v91, v11, v160
	v_exp_f32_e32 v91, v91
	v_add_f32_e32 v161, v161, v92
	v_bfi_b32 v91, v159, 0, v91
	s_waitcnt lgkmcnt(3)
	v_add_f32_e32 v94, v12, v132
	v_exp_f32_e32 v94, v94
	v_add_f32_e32 v161, v161, v91
	v_bfi_b32 v94, v131, 0, v94
	s_waitcnt lgkmcnt(2)
	v_add_f32_e32 v93, v13, v134
	v_exp_f32_e32 v93, v93
	v_add_f32_e32 v161, v161, v94
	v_bfi_b32 v93, v133, 0, v93
	s_waitcnt lgkmcnt(1)
	v_add_f32_e32 v130, v14, v136
	v_exp_f32_e32 v130, v130
	v_add_f32_e32 v161, v161, v93
	v_bfi_b32 v130, v135, 0, v130
	s_waitcnt lgkmcnt(0)
	v_add_f32_e32 v95, v15, v138
	v_exp_f32_e32 v95, v95
	v_add_f32_e32 v161, v161, v130
	v_bfi_b32 v95, v137, 0, v95
	v_add_f32_e32 v0, v161, v95
	v_readlane_b32 s0, v253, 1
	s_lshl_b32 s2, s0, 13
	ds_bpermute_b32 v1, v163, v0
	v_mul_f32_e32 v2, 0.5, v48
	ds_bpermute_b32 v2, v163, v2
	v_readlane_b32 s4, v251, 42
	v_readlane_b32 s5, v251, 43
	s_waitcnt lgkmcnt(1)
	v_add_f32_e32 v0, v0, v1
	v_div_scale_f32 v1, s[0:1], v0, v0, 1.0
	v_rcp_f32_e32 v3, v1
	v_div_scale_f32 v4, vcc, 1.0, v0, 1.0
	s_lshl_b32 s0, s2, 1
	v_fma_f32 v5, -v1, v3, 1.0
	v_fmac_f32_e32 v3, v5, v3
	v_mul_f32_e32 v5, v4, v3
	v_fma_f32 v6, -v1, v5, v4
	v_fmac_f32_e32 v5, v6, v3
	v_fma_f32 v1, -v1, v5, v4
	v_div_fmas_f32 v1, v1, v3, v5
	v_div_fixup_f32 v1, v1, v0, 1.0
	v_cmp_lt_f32_e32 vcc, 0, v0
	v_add_f32_e32 v0, v65, v64
	v_add_f32_e32 v3, v51, v50
	v_cndmask_b32_e32 v66, 0, v1, vcc
	v_fma_f32 v1, 0.5, v48, v49
	v_add_f32_e32 v0, v0, v1
	s_waitcnt lgkmcnt(0)
	v_cndmask_b32_e64 v1, v2, 0, s[4:5]
	v_add_f32_e32 v0, v0, v1
	v_mul_f32_e32 v1, 0.5, v52
	ds_bpermute_b32 v1, v163, v1
	v_fma_f32 v4, 0.5, v52, v53
	v_add_f32_e32 v3, v3, v4
	v_mul_f32_e32 v0, v66, v0
	v_fma_f32 v4, 0.5, v60, v61
	s_waitcnt lgkmcnt(0)
	v_cndmask_b32_e64 v2, v1, v2, s[4:5]
	v_add_f32_e32 v2, v3, v2
	v_mul_f32_e32 v3, 0.5, v56
	ds_bpermute_b32 v3, v163, v3
	v_mul_f32_e32 v2, v66, v2
	ds_write2_b32 v239, v0, v2 offset1:2
	v_add_f32_e32 v0, v55, v54
	v_fma_f32 v2, 0.5, v56, v57
	v_add_f32_e32 v0, v0, v2
	s_waitcnt lgkmcnt(1)
	v_cndmask_b32_e64 v1, v3, v1, s[4:5]
	v_add_f32_e32 v0, v0, v1
	v_mul_f32_e32 v1, 0.5, v60
	ds_bpermute_b32 v1, v163, v1
	v_add_f32_e32 v2, v59, v58
	v_add_f32_e32 v2, v2, v4
	v_mul_f32_e32 v0, v66, v0
	v_fma_f32 v4, 0.5, v36, v37
	s_waitcnt lgkmcnt(0)
	v_cndmask_b32_e64 v3, v1, v3, s[4:5]
	v_add_f32_e32 v2, v2, v3
	v_mul_f32_e32 v3, 0.5, v32
	ds_bpermute_b32 v3, v163, v3
	v_mul_f32_e32 v2, v66, v2
	ds_write2_b32 v239, v0, v2 offset0:4 offset1:6
	v_add_f32_e32 v0, v63, v62
	v_fma_f32 v2, 0.5, v32, v33
	v_add_f32_e32 v0, v0, v2
	s_waitcnt lgkmcnt(1)
	v_cndmask_b32_e64 v1, v3, v1, s[4:5]
	v_add_f32_e32 v0, v0, v1
	v_mul_f32_e32 v1, 0.5, v36
	ds_bpermute_b32 v1, v163, v1
	v_add_f32_e32 v2, v35, v34
	v_add_f32_e32 v2, v2, v4
	v_readlane_b32 s2, v252, 62
	v_mul_f32_e32 v0, v66, v0
	s_waitcnt lgkmcnt(0)
	v_cndmask_b32_e64 v3, v1, v3, s[4:5]
	v_add_f32_e32 v2, v2, v3
	v_mul_f32_e32 v3, 0.5, v40
	ds_bpermute_b32 v4, v163, v3
	v_mul_f32_e32 v2, v66, v2
	v_readlane_b32 s3, v252, 63
	s_add_u32 s0, s2, s0
	ds_write2_b32 v239, v0, v2 offset0:8 offset1:10
	v_add_f32_e32 v0, v39, v38
	v_fma_f32 v2, 0.5, v40, v41
	s_addc_u32 s1, s3, 0
	v_mov_b32_e32 v189, v97
	v_add_f32_e32 v5, v0, v2
	s_waitcnt lgkmcnt(1)
	v_cndmask_b32_e64 v6, v4, v1, s[4:5]
	v_lshl_add_u64 v[0:1], s[0:1], 0, v[188:189]
	s_mov_b64 s[0:1], 0x5200000
	v_lshl_add_u64 v[0:1], v[0:1], 0, s[0:1]
	v_mov_b32_e32 v191, v97
	v_lshl_add_u64 v[156:157], v[0:1], 0, v[190:191]
	v_mov_b32_e32 v193, v97
	v_lshl_add_u64 v[158:159], v[0:1], 0, v[192:193]
	global_load_dwordx2 v[0:1], v[156:157], off
	global_load_dwordx2 v[2:3], v[156:157], off offset:16
	global_load_dwordx2 v[132:133], v[156:157], off offset:32
	global_load_dwordx2 v[134:135], v[156:157], off offset:48
	global_load_dwordx2 v[16:17], v[158:159], off
	global_load_dwordx2 v[18:19], v[158:159], off offset:16
	global_load_dwordx2 v[136:137], v[158:159], off offset:32
	global_load_dwordx2 v[138:139], v[158:159], off offset:48
	global_load_dwordx2 v[140:141], v[156:157], off offset:64
	global_load_dwordx2 v[142:143], v[156:157], off offset:80
	global_load_dwordx2 v[144:145], v[156:157], off offset:96
	global_load_dwordx2 v[146:147], v[156:157], off offset:112
	global_load_dwordx2 v[148:149], v[158:159], off offset:64
	global_load_dwordx2 v[150:151], v[158:159], off offset:80
	global_load_dwordx2 v[152:153], v[158:159], off offset:96
	global_load_dwordx2 v[154:155], v[158:159], off offset:112
	v_add_f32_e32 v5, v5, v6
	v_mul_f32_e32 v6, 0.5, v68
	ds_bpermute_b32 v6, v163, v6
	v_add_f32_e32 v7, v67, v43
	v_fma_f32 v8, 0.5, v68, v69
	v_add_f32_e32 v7, v7, v8
	v_mul_f32_e32 v5, v66, v5
	s_waitcnt lgkmcnt(0)
	v_cndmask_b32_e64 v4, v6, v4, s[4:5]
	v_add_f32_e32 v4, v7, v4
	v_mul_f32_e32 v7, 0.5, v45
	ds_bpermute_b32 v7, v163, v7
	v_mul_f32_e32 v4, v66, v4
	ds_write2_b32 v239, v5, v4 offset0:12 offset1:14
	v_add_f32_e32 v4, v44, v42
	v_fma_f32 v5, 0.5, v45, v46
	v_add_f32_e32 v4, v4, v5
	s_waitcnt lgkmcnt(1)
	v_cndmask_b32_e64 v5, v7, v6, s[4:5]
	v_add_f32_e32 v4, v4, v5
	v_mul_f32_e32 v5, 0.5, v71
	ds_bpermute_b32 v5, v163, v5
	v_add_f32_e32 v6, v70, v47
	v_fma_f32 v8, 0.5, v71, v72
	v_add_f32_e32 v6, v6, v8
	v_mul_f32_e32 v4, v66, v4
	s_waitcnt lgkmcnt(0)
	v_cndmask_b32_e64 v7, v5, v7, s[4:5]
	v_add_f32_e32 v6, v6, v7
	v_mul_f32_e32 v7, 0.5, v75
	ds_bpermute_b32 v7, v163, v7
	v_mul_f32_e32 v6, v66, v6
	ds_write2_b32 v239, v4, v6 offset0:16 offset1:18
	v_add_f32_e32 v4, v74, v73
	v_fma_f32 v6, 0.5, v75, v76
	v_add_f32_e32 v4, v4, v6
	s_waitcnt lgkmcnt(1)
	v_cndmask_b32_e64 v5, v7, v5, s[4:5]
	v_add_f32_e32 v4, v4, v5
	v_mul_f32_e32 v5, 0.5, v79
	ds_bpermute_b32 v5, v163, v5
	v_add_f32_e32 v6, v78, v77
	v_fma_f32 v8, 0.5, v79, v80
	v_add_f32_e32 v6, v6, v8
	v_mul_f32_e32 v4, v66, v4
	s_waitcnt lgkmcnt(0)
	v_cndmask_b32_e64 v7, v5, v7, s[4:5]
	v_add_f32_e32 v6, v6, v7
	v_mul_f32_e32 v7, 0.5, v83
	ds_bpermute_b32 v7, v163, v7
	v_mul_f32_e32 v6, v66, v6
	ds_write2_b32 v239, v4, v6 offset0:20 offset1:22
	v_add_f32_e32 v4, v82, v81
	v_fma_f32 v6, 0.5, v83, v84
	v_add_f32_e32 v4, v4, v6
	s_waitcnt lgkmcnt(1)
	v_cndmask_b32_e64 v5, v7, v5, s[4:5]
	v_add_f32_e32 v4, v4, v5
	v_mul_f32_e32 v5, 0.5, v87
	ds_bpermute_b32 v5, v163, v5
	v_add_f32_e32 v6, v86, v85
	v_fma_f32 v8, 0.5, v87, v88
	v_add_f32_e32 v6, v6, v8
	v_mul_f32_e32 v4, v66, v4
	s_waitcnt lgkmcnt(0)
	v_cndmask_b32_e64 v7, v5, v7, s[4:5]
	v_add_f32_e32 v6, v6, v7
	v_mul_f32_e32 v7, 0.5, v91
	ds_bpermute_b32 v7, v163, v7
	v_mul_f32_e32 v6, v66, v6
	ds_write2_b32 v239, v4, v6 offset0:24 offset1:26
	v_add_f32_e32 v4, v90, v89
	v_fma_f32 v6, 0.5, v91, v92
	v_add_f32_e32 v4, v4, v6
	s_waitcnt lgkmcnt(1)
	v_cndmask_b32_e64 v5, v7, v5, s[4:5]
	v_add_f32_e32 v4, v4, v5
	v_mul_f32_e32 v5, 0.5, v95
	ds_bpermute_b32 v5, v163, v5
	v_add_f32_e32 v6, v94, v93
	v_fma_f32 v8, 0.5, v95, v130
	v_add_f32_e32 v6, v6, v8
	v_mul_f32_e32 v4, v66, v4
	s_waitcnt lgkmcnt(0)
	v_cndmask_b32_e64 v5, v5, v7, s[4:5]
	v_add_f32_e32 v5, v6, v5
	v_mul_f32_e32 v5, v66, v5
	ds_write2_b32 v239, v4, v5 offset0:28 offset1:30
	v_cvt_pk_bf16_f32 v20, v65, v64
	v_cvt_pk_bf16_f32 v21, v49, v48
	v_cvt_pk_bf16_f32 v22, v51, v50
	v_cvt_pk_bf16_f32 v23, v53, v52
	v_cvt_pk_bf16_f32 v48, v55, v54
	v_cvt_pk_bf16_f32 v49, v57, v56
	s_waitcnt vmcnt(14)
	v_mfma_f32_32x32x16_bf16 v[0:15], v[0:3], v[20:23], 0
	v_cvt_pk_bf16_f32 v50, v59, v58
	v_cvt_pk_bf16_f32 v51, v61, v60
	s_waitcnt vmcnt(10)
	v_mfma_f32_32x32x16_bf16 v[16:31], v[16:19], v[20:23], 0
	v_mfma_f32_32x32x16_bf16 v[0:15], v[132:135], v[48:51], v[0:15]
	s_waitcnt vmcnt(8)
	v_mfma_f32_32x32x16_bf16 v[16:31], v[136:139], v[48:51], v[16:31]
	v_cvt_pk_bf16_f32 v48, v63, v62
	v_cvt_pk_bf16_f32 v49, v33, v32
	v_cvt_pk_bf16_f32 v50, v35, v34
	v_cvt_pk_bf16_f32 v51, v37, v36
	v_cvt_pk_bf16_f32 v32, v39, v38
	v_cvt_pk_bf16_f32 v33, v41, v40
	v_cvt_pk_bf16_f32 v34, v67, v43
	s_waitcnt vmcnt(6)
	v_mfma_f32_32x32x16_bf16 v[0:15], v[140:143], v[48:51], v[0:15]
	v_cvt_pk_bf16_f32 v35, v69, v68
	s_waitcnt vmcnt(2)
	v_mfma_f32_32x32x16_bf16 v[16:31], v[148:151], v[48:51], v[16:31]
	v_mfma_f32_32x32x16_bf16 v[0:15], v[144:147], v[32:35], v[0:15]
	s_waitcnt vmcnt(0)
	v_mfma_f32_32x32x16_bf16 v[16:31], v[152:155], v[32:35], v[16:31]
	global_load_dwordx2 v[32:33], v[156:157], off offset:128
	global_load_dwordx2 v[34:35], v[156:157], off offset:144
	global_load_dwordx2 v[36:37], v[158:159], off offset:128
	global_load_dwordx2 v[38:39], v[158:159], off offset:144
	global_load_dwordx2 v[48:49], v[156:157], off offset:160
	global_load_dwordx2 v[50:51], v[156:157], off offset:176
	global_load_dwordx2 v[52:53], v[158:159], off offset:160
	global_load_dwordx2 v[54:55], v[158:159], off offset:176
	global_load_dwordx2 v[56:57], v[156:157], off offset:192
	global_load_dwordx2 v[58:59], v[156:157], off offset:208
	global_load_dwordx2 v[60:61], v[158:159], off offset:192
	global_load_dwordx2 v[62:63], v[158:159], off offset:208
	global_load_dwordx2 v[132:133], v[156:157], off offset:224
	global_load_dwordx2 v[134:135], v[156:157], off offset:240
	global_load_dwordx2 v[136:137], v[158:159], off offset:224
	global_load_dwordx2 v[138:139], v[158:159], off offset:240
	v_cvt_pk_bf16_f32 v40, v44, v42
	v_cvt_pk_bf16_f32 v41, v46, v45
	v_cvt_pk_bf16_f32 v42, v70, v47
	v_cvt_pk_bf16_f32 v43, v72, v71
	v_readlane_b32 s0, v251, 44
	v_readlane_b32 s1, v251, 45
	s_waitcnt vmcnt(14)
	v_mfma_f32_32x32x16_bf16 v[0:15], v[32:35], v[40:43], v[0:15]
	v_cvt_pk_bf16_f32 v32, v74, v73
	v_cvt_pk_bf16_f32 v33, v76, v75
	v_cvt_pk_bf16_f32 v34, v78, v77
	v_cvt_pk_bf16_f32 v35, v80, v79
	s_mov_b64 s[14:15], -1
	s_mov_b64 s[12:13], -1
	s_waitcnt vmcnt(12)
	v_mfma_f32_32x32x16_bf16 v[16:31], v[36:39], v[40:43], v[16:31]
	s_waitcnt vmcnt(10)
	v_mfma_f32_32x32x16_bf16 v[0:15], v[48:51], v[32:35], v[0:15]
	s_waitcnt vmcnt(8)
	v_mfma_f32_32x32x16_bf16 v[16:31], v[52:55], v[32:35], v[16:31]
	v_cvt_pk_bf16_f32 v32, v82, v81
	v_cvt_pk_bf16_f32 v33, v84, v83
	v_cvt_pk_bf16_f32 v34, v86, v85
	v_cvt_pk_bf16_f32 v35, v88, v87
	s_waitcnt vmcnt(6)
	s_nop 0
	v_mfma_f32_32x32x16_bf16 v[0:15], v[56:59], v[32:35], v[0:15]
	s_waitcnt vmcnt(4)
	v_mfma_f32_32x32x16_bf16 v[16:31], v[60:63], v[32:35], v[16:31]
	v_cvt_pk_bf16_f32 v32, v90, v89
	v_cvt_pk_bf16_f32 v33, v92, v91
	v_cvt_pk_bf16_f32 v34, v94, v93
	v_cvt_pk_bf16_f32 v35, v130, v95
	s_waitcnt vmcnt(2)
	s_nop 0
	v_mfma_f32_32x32x16_bf16 v[0:15], v[132:135], v[32:35], v[0:15]
	s_waitcnt vmcnt(0)
	v_mfma_f32_32x32x16_bf16 v[16:31], v[136:139], v[32:35], v[16:31]
	v_mul_f32_e32 v32, v162, v66
	s_nop 8
	v_mul_f32_e32 v0, v32, v0
	v_mul_f32_e32 v1, v32, v1
	ds_write2st64_b32 v173, v0, v1 offset1:1
	v_mul_f32_e32 v16, v32, v16
	v_mul_f32_e32 v0, v32, v17
	ds_write2st64_b32 v173, v16, v0 offset0:16 offset1:17
	v_mul_f32_e32 v0, v32, v2
	v_mul_f32_e32 v2, v32, v3
	v_mul_f32_e32 v1, v32, v18
	ds_write2st64_b32 v173, v0, v2 offset0:2 offset1:3
	v_mul_f32_e32 v0, v32, v19
	ds_write2st64_b32 v173, v1, v0 offset0:18 offset1:19
	v_mul_f32_e32 v0, v32, v4
	v_mul_f32_e32 v2, v32, v5
	v_mul_f32_e32 v1, v32, v20
	ds_write2st64_b32 v173, v0, v2 offset0:4 offset1:5
	v_mul_f32_e32 v0, v32, v21
	ds_write2st64_b32 v173, v1, v0 offset0:20 offset1:21
	v_mul_f32_e32 v0, v32, v6
	v_mul_f32_e32 v2, v32, v7
	v_mul_f32_e32 v1, v32, v22
	ds_write2st64_b32 v173, v0, v2 offset0:6 offset1:7
	v_mul_f32_e32 v0, v32, v23
	ds_write2st64_b32 v173, v1, v0 offset0:22 offset1:23
	v_mul_f32_e32 v0, v32, v8
	v_mul_f32_e32 v2, v32, v9
	v_mul_f32_e32 v1, v32, v24
	ds_write2st64_b32 v173, v0, v2 offset0:8 offset1:9
	v_mul_f32_e32 v0, v32, v25
	ds_write2st64_b32 v173, v1, v0 offset0:24 offset1:25
	v_mul_f32_e32 v0, v32, v10
	v_mul_f32_e32 v2, v32, v11
	v_mul_f32_e32 v1, v32, v26
	ds_write2st64_b32 v173, v0, v2 offset0:10 offset1:11
	v_mul_f32_e32 v0, v32, v27
	ds_write2st64_b32 v173, v1, v0 offset0:26 offset1:27
	v_mul_f32_e32 v0, v32, v12
	v_mul_f32_e32 v2, v32, v13
	v_mul_f32_e32 v1, v32, v28
	ds_write2st64_b32 v173, v0, v2 offset0:12 offset1:13
	v_mul_f32_e32 v0, v32, v29
	ds_write2st64_b32 v173, v1, v0 offset0:28 offset1:29
	v_mul_f32_e32 v0, v32, v14
	v_mul_f32_e32 v2, v32, v15
	v_mul_f32_e32 v1, v32, v30
	ds_write2st64_b32 v173, v0, v2 offset0:14 offset1:15
	v_mul_f32_e32 v0, v32, v31
	ds_write2st64_b32 v173, v1, v0 offset0:30 offset1:31
	s_waitcnt lgkmcnt(0)
	s_barrier
	s_add_i32 s51, s50, -2
	s_lshl_b32 s16, 1, s50
	s_lshr_b32 s17, s16, 1
	s_or_b32 s16, s16, s17
	s_or_b32 s16, s16, 1
	s_bcnt1_i32_b32 s17, s16
	s_sub_i32 s17, 8, s17
	s_max_i32 s18, s51, 0
	v_lshl_add_u32 v134, v177, 2, v240
	ds_read_b128 v[80:83], v134
	ds_read_b128 v[84:87], v134 offset:9216
	ds_read_b128 v[88:91], v134 offset:18432
	ds_read_b128 v[92:95], v134 offset:27648
	ds_read_b128 v[32:35], v240
	ds_read_b128 v[36:39], v240 offset:9216
	ds_read_b128 v[40:43], v240 offset:18432
	ds_read_b128 v[44:47], v240 offset:27648
	ds_read_b128 v[48:51], v240 offset:16
	ds_read_b128 v[52:55], v240 offset:9232
	ds_read_b128 v[56:59], v240 offset:18448
	ds_read_b128 v[60:63], v240 offset:27664
	s_waitcnt lgkmcnt(8)
	v_pk_add_f32 v[80:81], v[80:81], v[84:85]
	v_pk_add_f32 v[82:83], v[82:83], v[86:87]
	v_pk_add_f32 v[88:89], v[88:89], v[92:93]
	v_pk_add_f32 v[90:91], v[90:91], v[94:95]
	v_pk_add_f32 v[80:81], v[80:81], v[88:89]
	v_pk_add_f32 v[82:83], v[82:83], v[90:91]
	ds_read_b128 v[64:67], v240 offset:32
	ds_read_b128 v[68:71], v240 offset:9248
	ds_read_b128 v[72:75], v240 offset:18464
	ds_read_b128 v[76:79], v240 offset:27680
	v_add_u32_e32 v140, -1, v177
	v_add_u32_e32 v141, 0, v177
	v_add_u32_e32 v142, 1, v177
	v_add_u32_e32 v143, 2, v177
	v_cmp_gt_u32_e64 s[20:21], s18, v140
	v_cmp_gt_u32_e64 s[22:23], s18, v141
	v_cmp_gt_u32_e64 s[24:25], s18, v142
	v_cmp_gt_u32_e64 s[26:27], s18, v143
	v_mov_b32_e32 v136, 0
	v_mov_b32_e32 v137, 0
	v_mov_b32_e32 v138, 0
	v_mov_b32_e32 v139, 0
	v_cndmask_b32_e64 v80, -1, v80, s[20:21]
	v_cndmask_b32_e64 v81, -1, v81, s[22:23]
	v_cndmask_b32_e64 v82, -1, v82, s[24:25]
	v_cndmask_b32_e64 v83, -1, v83, s[26:27]
	v_add_u32_e32 v84, -1, v80
	v_add_u32_e32 v85, -1, v81
	v_add_u32_e32 v86, -1, v82
	v_add_u32_e32 v87, -1, v83
	s_waitcnt lgkmcnt(8)
	v_pk_add_f32 v[32:33], v[32:33], v[36:37]
	v_pk_add_f32 v[34:35], v[34:35], v[38:39]
	v_pk_add_f32 v[40:41], v[40:41], v[44:45]
	v_pk_add_f32 v[42:43], v[42:43], v[46:47]
	v_pk_add_f32 v[0:1], v[32:33], v[40:41]
	v_pk_add_f32 v[2:3], v[34:35], v[42:43]
	ds_read_b128 v[32:35], v240 offset:48
	ds_read_b128 v[36:39], v240 offset:9264
	ds_read_b128 v[40:43], v240 offset:18480
	ds_read_b128 v[44:47], v240 offset:27696
	v_cmp_le_u32_e64 s[30:31], 4, v177
	s_cmp_gt_i32 s18, 0
	s_cselect_b64 s[28:29], -1, 0
	v_cndmask_b32_e64 v1, -1, v1, s[28:29]
	s_cmp_gt_i32 s18, 1
	s_cselect_b64 s[28:29], -1, 0
	v_cndmask_b32_e64 v2, -1, v2, s[28:29]
	s_cmp_gt_i32 s18, 2
	s_cselect_b64 s[28:29], -1, 0
	v_cndmask_b32_e64 v3, -1, v3, s[28:29]
	v_cndmask_b32_e64 v92, v80, v84, s[30:31]
	v_cndmask_b32_e64 v93, v81, v85, s[30:31]
	v_cndmask_b32_e64 v94, v82, v86, s[30:31]
	v_cndmask_b32_e64 v95, v83, v87, s[30:31]
	v_cmp_gt_i32_e64 s[38:39], v1, v92
	v_cmp_gt_i32_e64 s[40:41], v1, v93
	v_cmp_gt_i32_e64 s[42:43], v1, v86
	v_cmp_gt_i32_e64 s[44:45], v1, v87
	v_addc_co_u32_e64 v136, s[36:37], 0, v136, s[38:39]
	v_addc_co_u32_e64 v137, s[36:37], 0, v137, s[40:41]
	v_addc_co_u32_e64 v138, s[36:37], 0, v138, s[42:43]
	v_addc_co_u32_e64 v139, s[36:37], 0, v139, s[44:45]
	v_cmp_gt_i32_e64 s[38:39], v2, v92
	v_cmp_gt_i32_e64 s[40:41], v2, v93
	v_cmp_gt_i32_e64 s[42:43], v2, v94
	v_cmp_gt_i32_e64 s[44:45], v2, v87
	v_addc_co_u32_e64 v136, s[36:37], 0, v136, s[38:39]
	v_addc_co_u32_e64 v137, s[36:37], 0, v137, s[40:41]
	v_addc_co_u32_e64 v138, s[36:37], 0, v138, s[42:43]
	v_addc_co_u32_e64 v139, s[36:37], 0, v139, s[44:45]
	v_cmp_gt_i32_e64 s[38:39], v3, v92
	v_cmp_gt_i32_e64 s[40:41], v3, v93
	v_cmp_gt_i32_e64 s[42:43], v3, v94
	v_cmp_gt_i32_e64 s[44:45], v3, v95
	v_addc_co_u32_e64 v136, s[36:37], 0, v136, s[38:39]
	v_addc_co_u32_e64 v137, s[36:37], 0, v137, s[40:41]
	v_addc_co_u32_e64 v138, s[36:37], 0, v138, s[42:43]
	v_addc_co_u32_e64 v139, s[36:37], 0, v139, s[44:45]
	s_waitcnt lgkmcnt(8)
	v_pk_add_f32 v[48:49], v[48:49], v[52:53]
	v_pk_add_f32 v[50:51], v[50:51], v[54:55]
	v_pk_add_f32 v[56:57], v[56:57], v[60:61]
	v_pk_add_f32 v[58:59], v[58:59], v[62:63]
	v_pk_add_f32 v[4:5], v[48:49], v[56:57]
	v_pk_add_f32 v[6:7], v[50:51], v[58:59]
	ds_read_b128 v[48:51], v240 offset:64
	ds_read_b128 v[52:55], v240 offset:9280
	ds_read_b128 v[56:59], v240 offset:18496
	ds_read_b128 v[60:63], v240 offset:27712
	v_cmp_le_u32_e64 s[30:31], 8, v177
	s_cmp_gt_i32 s18, 3
	s_cselect_b64 s[28:29], -1, 0
	v_cndmask_b32_e64 v4, -1, v4, s[28:29]
	s_cmp_gt_i32 s18, 4
	s_cselect_b64 s[28:29], -1, 0
	v_cndmask_b32_e64 v5, -1, v5, s[28:29]
	s_cmp_gt_i32 s18, 5
	s_cselect_b64 s[28:29], -1, 0
	v_cndmask_b32_e64 v6, -1, v6, s[28:29]
	s_cmp_gt_i32 s18, 6
	s_cselect_b64 s[28:29], -1, 0
	v_cndmask_b32_e64 v7, -1, v7, s[28:29]
	v_cndmask_b32_e64 v88, v80, v84, s[30:31]
	v_cndmask_b32_e64 v89, v81, v85, s[30:31]
	v_cndmask_b32_e64 v90, v82, v86, s[30:31]
	v_cndmask_b32_e64 v91, v83, v87, s[30:31]
	v_cmp_gt_i32_e64 s[38:39], v4, v88
	v_cmp_gt_i32_e64 s[40:41], v4, v93
	v_cmp_gt_i32_e64 s[42:43], v4, v94
	v_cmp_gt_i32_e64 s[44:45], v4, v95
	v_addc_co_u32_e64 v136, s[36:37], 0, v136, s[38:39]
	v_addc_co_u32_e64 v137, s[36:37], 0, v137, s[40:41]
	v_addc_co_u32_e64 v138, s[36:37], 0, v138, s[42:43]
	v_addc_co_u32_e64 v139, s[36:37], 0, v139, s[44:45]
	v_cmp_gt_i32_e64 s[38:39], v5, v88
	v_cmp_gt_i32_e64 s[40:41], v5, v89
	v_cmp_gt_i32_e64 s[42:43], v5, v94
	v_cmp_gt_i32_e64 s[44:45], v5, v95
	v_addc_co_u32_e64 v136, s[36:37], 0, v136, s[38:39]
	v_addc_co_u32_e64 v137, s[36:37], 0, v137, s[40:41]
	v_addc_co_u32_e64 v138, s[36:37], 0, v138, s[42:43]
	v_addc_co_u32_e64 v139, s[36:37], 0, v139, s[44:45]
	v_cmp_gt_i32_e64 s[38:39], v6, v88
	v_cmp_gt_i32_e64 s[40:41], v6, v89
	v_cmp_gt_i32_e64 s[42:43], v6, v90
	v_cmp_gt_i32_e64 s[44:45], v6, v95
	v_addc_co_u32_e64 v136, s[36:37], 0, v136, s[38:39]
	v_addc_co_u32_e64 v137, s[36:37], 0, v137, s[40:41]
	v_addc_co_u32_e64 v138, s[36:37], 0, v138, s[42:43]
	v_addc_co_u32_e64 v139, s[36:37], 0, v139, s[44:45]
	v_cmp_gt_i32_e64 s[38:39], v7, v88
	v_cmp_gt_i32_e64 s[40:41], v7, v89
	v_cmp_gt_i32_e64 s[42:43], v7, v90
	v_cmp_gt_i32_e64 s[44:45], v7, v91
	v_addc_co_u32_e64 v136, s[36:37], 0, v136, s[38:39]
	v_addc_co_u32_e64 v137, s[36:37], 0, v137, s[40:41]
	v_addc_co_u32_e64 v138, s[36:37], 0, v138, s[42:43]
	v_addc_co_u32_e64 v139, s[36:37], 0, v139, s[44:45]
	s_waitcnt lgkmcnt(8)
	v_pk_add_f32 v[64:65], v[64:65], v[68:69]
	v_pk_add_f32 v[66:67], v[66:67], v[70:71]
	v_pk_add_f32 v[72:73], v[72:73], v[76:77]
	v_pk_add_f32 v[74:75], v[74:75], v[78:79]
	v_pk_add_f32 v[8:9], v[64:65], v[72:73]
	v_pk_add_f32 v[10:11], v[66:67], v[74:75]
	ds_read_b128 v[64:67], v240 offset:80
	ds_read_b128 v[68:71], v240 offset:9296
	ds_read_b128 v[72:75], v240 offset:18512
	ds_read_b128 v[76:79], v240 offset:27728
	v_cmp_le_u32_e64 s[30:31], 12, v177
	s_cmp_gt_i32 s18, 7
	s_cselect_b64 s[28:29], -1, 0
	v_cndmask_b32_e64 v8, -1, v8, s[28:29]
	s_cmp_gt_i32 s18, 8
	s_cselect_b64 s[28:29], -1, 0
	v_cndmask_b32_e64 v9, -1, v9, s[28:29]
	s_cmp_gt_i32 s18, 9
	s_cselect_b64 s[28:29], -1, 0
	v_cndmask_b32_e64 v10, -1, v10, s[28:29]
	s_cmp_gt_i32 s18, 10
	s_cselect_b64 s[28:29], -1, 0
	v_cndmask_b32_e64 v11, -1, v11, s[28:29]
	v_cndmask_b32_e64 v92, v80, v84, s[30:31]
	v_cndmask_b32_e64 v93, v81, v85, s[30:31]
	v_cndmask_b32_e64 v94, v82, v86, s[30:31]
	v_cndmask_b32_e64 v95, v83, v87, s[30:31]
	v_cmp_gt_i32_e64 s[38:39], v8, v92
	v_cmp_gt_i32_e64 s[40:41], v8, v89
	v_cmp_gt_i32_e64 s[42:43], v8, v90
	v_cmp_gt_i32_e64 s[44:45], v8, v91
	v_addc_co_u32_e64 v136, s[36:37], 0, v136, s[38:39]
	v_addc_co_u32_e64 v137, s[36:37], 0, v137, s[40:41]
	v_addc_co_u32_e64 v138, s[36:37], 0, v138, s[42:43]
	v_addc_co_u32_e64 v139, s[36:37], 0, v139, s[44:45]
	v_cmp_gt_i32_e64 s[38:39], v9, v92
	v_cmp_gt_i32_e64 s[40:41], v9, v93
	v_cmp_gt_i32_e64 s[42:43], v9, v90
	v_cmp_gt_i32_e64 s[44:45], v9, v91
	v_addc_co_u32_e64 v136, s[36:37], 0, v136, s[38:39]
	v_addc_co_u32_e64 v137, s[36:37], 0, v137, s[40:41]
	v_addc_co_u32_e64 v138, s[36:37], 0, v138, s[42:43]
	v_addc_co_u32_e64 v139, s[36:37], 0, v139, s[44:45]
	v_cmp_gt_i32_e64 s[38:39], v10, v92
	v_cmp_gt_i32_e64 s[40:41], v10, v93
	v_cmp_gt_i32_e64 s[42:43], v10, v94
	v_cmp_gt_i32_e64 s[44:45], v10, v91
	v_addc_co_u32_e64 v136, s[36:37], 0, v136, s[38:39]
	v_addc_co_u32_e64 v137, s[36:37], 0, v137, s[40:41]
	v_addc_co_u32_e64 v138, s[36:37], 0, v138, s[42:43]
	v_addc_co_u32_e64 v139, s[36:37], 0, v139, s[44:45]
	v_cmp_gt_i32_e64 s[38:39], v11, v92
	v_cmp_gt_i32_e64 s[40:41], v11, v93
	v_cmp_gt_i32_e64 s[42:43], v11, v94
	v_cmp_gt_i32_e64 s[44:45], v11, v95
	v_addc_co_u32_e64 v136, s[36:37], 0, v136, s[38:39]
	v_addc_co_u32_e64 v137, s[36:37], 0, v137, s[40:41]
	v_addc_co_u32_e64 v138, s[36:37], 0, v138, s[42:43]
	v_addc_co_u32_e64 v139, s[36:37], 0, v139, s[44:45]
	s_waitcnt lgkmcnt(8)
	v_pk_add_f32 v[32:33], v[32:33], v[36:37]
	v_pk_add_f32 v[34:35], v[34:35], v[38:39]
	v_pk_add_f32 v[40:41], v[40:41], v[44:45]
	v_pk_add_f32 v[42:43], v[42:43], v[46:47]
	v_pk_add_f32 v[12:13], v[32:33], v[40:41]
	v_pk_add_f32 v[14:15], v[34:35], v[42:43]
	ds_read_b128 v[32:35], v240 offset:96
	ds_read_b128 v[36:39], v240 offset:9312
	ds_read_b128 v[40:43], v240 offset:18528
	ds_read_b128 v[44:47], v240 offset:27744
	v_cmp_le_u32_e64 s[30:31], 16, v177
	s_cmp_gt_i32 s18, 11
	s_cselect_b64 s[28:29], -1, 0
	v_cndmask_b32_e64 v12, -1, v12, s[28:29]
	s_cmp_gt_i32 s18, 12
	s_cselect_b64 s[28:29], -1, 0
	v_cndmask_b32_e64 v13, -1, v13, s[28:29]
	s_cmp_gt_i32 s18, 13
	s_cselect_b64 s[28:29], -1, 0
	v_cndmask_b32_e64 v14, -1, v14, s[28:29]
	s_cmp_gt_i32 s18, 14
	s_cselect_b64 s[28:29], -1, 0
	v_cndmask_b32_e64 v15, -1, v15, s[28:29]
	v_cndmask_b32_e64 v88, v80, v84, s[30:31]
	v_cndmask_b32_e64 v89, v81, v85, s[30:31]
	v_cndmask_b32_e64 v90, v82, v86, s[30:31]
	v_cndmask_b32_e64 v91, v83, v87, s[30:31]
	v_cmp_gt_i32_e64 s[38:39], v12, v88
	v_cmp_gt_i32_e64 s[40:41], v12, v93
	v_cmp_gt_i32_e64 s[42:43], v12, v94
	v_cmp_gt_i32_e64 s[44:45], v12, v95
	v_addc_co_u32_e64 v136, s[36:37], 0, v136, s[38:39]
	v_addc_co_u32_e64 v137, s[36:37], 0, v137, s[40:41]
	v_addc_co_u32_e64 v138, s[36:37], 0, v138, s[42:43]
	v_addc_co_u32_e64 v139, s[36:37], 0, v139, s[44:45]
	v_cmp_gt_i32_e64 s[38:39], v13, v88
	v_cmp_gt_i32_e64 s[40:41], v13, v89
	v_cmp_gt_i32_e64 s[42:43], v13, v94
	v_cmp_gt_i32_e64 s[44:45], v13, v95
	v_addc_co_u32_e64 v136, s[36:37], 0, v136, s[38:39]
	v_addc_co_u32_e64 v137, s[36:37], 0, v137, s[40:41]
	v_addc_co_u32_e64 v138, s[36:37], 0, v138, s[42:43]
	v_addc_co_u32_e64 v139, s[36:37], 0, v139, s[44:45]
	v_cmp_gt_i32_e64 s[38:39], v14, v88
	v_cmp_gt_i32_e64 s[40:41], v14, v89
	v_cmp_gt_i32_e64 s[42:43], v14, v90
	v_cmp_gt_i32_e64 s[44:45], v14, v95
	v_addc_co_u32_e64 v136, s[36:37], 0, v136, s[38:39]
	v_addc_co_u32_e64 v137, s[36:37], 0, v137, s[40:41]
	v_addc_co_u32_e64 v138, s[36:37], 0, v138, s[42:43]
	v_addc_co_u32_e64 v139, s[36:37], 0, v139, s[44:45]
	v_cmp_gt_i32_e64 s[38:39], v15, v88
	v_cmp_gt_i32_e64 s[40:41], v15, v89
	v_cmp_gt_i32_e64 s[42:43], v15, v90
	v_cmp_gt_i32_e64 s[44:45], v15, v91
	v_addc_co_u32_e64 v136, s[36:37], 0, v136, s[38:39]
	v_addc_co_u32_e64 v137, s[36:37], 0, v137, s[40:41]
	v_addc_co_u32_e64 v138, s[36:37], 0, v138, s[42:43]
	v_addc_co_u32_e64 v139, s[36:37], 0, v139, s[44:45]
	s_waitcnt lgkmcnt(8)
	v_pk_add_f32 v[48:49], v[48:49], v[52:53]
	v_pk_add_f32 v[50:51], v[50:51], v[54:55]
	v_pk_add_f32 v[56:57], v[56:57], v[60:61]
	v_pk_add_f32 v[58:59], v[58:59], v[62:63]
	v_pk_add_f32 v[16:17], v[48:49], v[56:57]
	v_pk_add_f32 v[18:19], v[50:51], v[58:59]
	ds_read_b128 v[48:51], v240 offset:112
	ds_read_b128 v[52:55], v240 offset:9328
	ds_read_b128 v[56:59], v240 offset:18544
	ds_read_b128 v[60:63], v240 offset:27760
	v_cmp_le_u32_e64 s[30:31], 20, v177
	s_cmp_gt_i32 s18, 15
	s_cselect_b64 s[28:29], -1, 0
	v_cndmask_b32_e64 v16, -1, v16, s[28:29]
	s_cmp_gt_i32 s18, 16
	s_cselect_b64 s[28:29], -1, 0
	v_cndmask_b32_e64 v17, -1, v17, s[28:29]
	s_cmp_gt_i32 s18, 17
	s_cselect_b64 s[28:29], -1, 0
	v_cndmask_b32_e64 v18, -1, v18, s[28:29]
	s_cmp_gt_i32 s18, 18
	s_cselect_b64 s[28:29], -1, 0
	v_cndmask_b32_e64 v19, -1, v19, s[28:29]
	v_cndmask_b32_e64 v92, v80, v84, s[30:31]
	v_cndmask_b32_e64 v93, v81, v85, s[30:31]
	v_cndmask_b32_e64 v94, v82, v86, s[30:31]
	v_cndmask_b32_e64 v95, v83, v87, s[30:31]
	v_cmp_gt_i32_e64 s[38:39], v16, v92
	v_cmp_gt_i32_e64 s[40:41], v16, v89
	v_cmp_gt_i32_e64 s[42:43], v16, v90
	v_cmp_gt_i32_e64 s[44:45], v16, v91
	v_addc_co_u32_e64 v136, s[36:37], 0, v136, s[38:39]
	v_addc_co_u32_e64 v137, s[36:37], 0, v137, s[40:41]
	v_addc_co_u32_e64 v138, s[36:37], 0, v138, s[42:43]
	v_addc_co_u32_e64 v139, s[36:37], 0, v139, s[44:45]
	v_cmp_gt_i32_e64 s[38:39], v17, v92
	v_cmp_gt_i32_e64 s[40:41], v17, v93
	v_cmp_gt_i32_e64 s[42:43], v17, v90
	v_cmp_gt_i32_e64 s[44:45], v17, v91
	v_addc_co_u32_e64 v136, s[36:37], 0, v136, s[38:39]
	v_addc_co_u32_e64 v137, s[36:37], 0, v137, s[40:41]
	v_addc_co_u32_e64 v138, s[36:37], 0, v138, s[42:43]
	v_addc_co_u32_e64 v139, s[36:37], 0, v139, s[44:45]
	v_cmp_gt_i32_e64 s[38:39], v18, v92
	v_cmp_gt_i32_e64 s[40:41], v18, v93
	v_cmp_gt_i32_e64 s[42:43], v18, v94
	v_cmp_gt_i32_e64 s[44:45], v18, v91
	v_addc_co_u32_e64 v136, s[36:37], 0, v136, s[38:39]
	v_addc_co_u32_e64 v137, s[36:37], 0, v137, s[40:41]
	v_addc_co_u32_e64 v138, s[36:37], 0, v138, s[42:43]
	v_addc_co_u32_e64 v139, s[36:37], 0, v139, s[44:45]
	v_cmp_gt_i32_e64 s[38:39], v19, v92
	v_cmp_gt_i32_e64 s[40:41], v19, v93
	v_cmp_gt_i32_e64 s[42:43], v19, v94
	v_cmp_gt_i32_e64 s[44:45], v19, v95
	v_addc_co_u32_e64 v136, s[36:37], 0, v136, s[38:39]
	v_addc_co_u32_e64 v137, s[36:37], 0, v137, s[40:41]
	v_addc_co_u32_e64 v138, s[36:37], 0, v138, s[42:43]
	v_addc_co_u32_e64 v139, s[36:37], 0, v139, s[44:45]
	s_waitcnt lgkmcnt(8)
	v_pk_add_f32 v[64:65], v[64:65], v[68:69]
	v_pk_add_f32 v[66:67], v[66:67], v[70:71]
	v_pk_add_f32 v[72:73], v[72:73], v[76:77]
	v_pk_add_f32 v[74:75], v[74:75], v[78:79]
	v_pk_add_f32 v[20:21], v[64:65], v[72:73]
	v_pk_add_f32 v[22:23], v[66:67], v[74:75]
	v_cmp_le_u32_e64 s[30:31], 24, v177
	s_cmp_gt_i32 s18, 19
	s_cselect_b64 s[28:29], -1, 0
	v_cndmask_b32_e64 v20, -1, v20, s[28:29]
	s_cmp_gt_i32 s18, 20
	s_cselect_b64 s[28:29], -1, 0
	v_cndmask_b32_e64 v21, -1, v21, s[28:29]
	s_cmp_gt_i32 s18, 21
	s_cselect_b64 s[28:29], -1, 0
	v_cndmask_b32_e64 v22, -1, v22, s[28:29]
	s_cmp_gt_i32 s18, 22
	s_cselect_b64 s[28:29], -1, 0
	v_cndmask_b32_e64 v23, -1, v23, s[28:29]
	v_cndmask_b32_e64 v88, v80, v84, s[30:31]
	v_cndmask_b32_e64 v89, v81, v85, s[30:31]
	v_cndmask_b32_e64 v90, v82, v86, s[30:31]
	v_cndmask_b32_e64 v91, v83, v87, s[30:31]
	v_cmp_gt_i32_e64 s[38:39], v20, v88
	v_cmp_gt_i32_e64 s[40:41], v20, v93
	v_cmp_gt_i32_e64 s[42:43], v20, v94
	v_cmp_gt_i32_e64 s[44:45], v20, v95
	v_addc_co_u32_e64 v136, s[36:37], 0, v136, s[38:39]
	v_addc_co_u32_e64 v137, s[36:37], 0, v137, s[40:41]
	v_addc_co_u32_e64 v138, s[36:37], 0, v138, s[42:43]
	v_addc_co_u32_e64 v139, s[36:37], 0, v139, s[44:45]
	v_cmp_gt_i32_e64 s[38:39], v21, v88
	v_cmp_gt_i32_e64 s[40:41], v21, v89
	v_cmp_gt_i32_e64 s[42:43], v21, v94
	v_cmp_gt_i32_e64 s[44:45], v21, v95
	v_addc_co_u32_e64 v136, s[36:37], 0, v136, s[38:39]
	v_addc_co_u32_e64 v137, s[36:37], 0, v137, s[40:41]
	v_addc_co_u32_e64 v138, s[36:37], 0, v138, s[42:43]
	v_addc_co_u32_e64 v139, s[36:37], 0, v139, s[44:45]
	v_cmp_gt_i32_e64 s[38:39], v22, v88
	v_cmp_gt_i32_e64 s[40:41], v22, v89
	v_cmp_gt_i32_e64 s[42:43], v22, v90
	v_cmp_gt_i32_e64 s[44:45], v22, v95
	v_addc_co_u32_e64 v136, s[36:37], 0, v136, s[38:39]
	v_addc_co_u32_e64 v137, s[36:37], 0, v137, s[40:41]
	v_addc_co_u32_e64 v138, s[36:37], 0, v138, s[42:43]
	v_addc_co_u32_e64 v139, s[36:37], 0, v139, s[44:45]
	v_cmp_gt_i32_e64 s[38:39], v23, v88
	v_cmp_gt_i32_e64 s[40:41], v23, v89
	v_cmp_gt_i32_e64 s[42:43], v23, v90
	v_cmp_gt_i32_e64 s[44:45], v23, v91
	v_addc_co_u32_e64 v136, s[36:37], 0, v136, s[38:39]
	v_addc_co_u32_e64 v137, s[36:37], 0, v137, s[40:41]
	v_addc_co_u32_e64 v138, s[36:37], 0, v138, s[42:43]
	v_addc_co_u32_e64 v139, s[36:37], 0, v139, s[44:45]
	s_waitcnt lgkmcnt(4)
	v_pk_add_f32 v[32:33], v[32:33], v[36:37]
	v_pk_add_f32 v[34:35], v[34:35], v[38:39]
	v_pk_add_f32 v[40:41], v[40:41], v[44:45]
	v_pk_add_f32 v[42:43], v[42:43], v[46:47]
	v_pk_add_f32 v[24:25], v[32:33], v[40:41]
	v_pk_add_f32 v[26:27], v[34:35], v[42:43]
	v_cmp_le_u32_e64 s[30:31], 28, v177
	s_cmp_gt_i32 s18, 23
	s_cselect_b64 s[28:29], -1, 0
	v_cndmask_b32_e64 v24, -1, v24, s[28:29]
	s_cmp_gt_i32 s18, 24
	s_cselect_b64 s[28:29], -1, 0
	v_cndmask_b32_e64 v25, -1, v25, s[28:29]
	s_cmp_gt_i32 s18, 25
	s_cselect_b64 s[28:29], -1, 0
	v_cndmask_b32_e64 v26, -1, v26, s[28:29]
	s_cmp_gt_i32 s18, 26
	s_cselect_b64 s[28:29], -1, 0
	v_cndmask_b32_e64 v27, -1, v27, s[28:29]
	v_cndmask_b32_e64 v92, v80, v84, s[30:31]
	v_cndmask_b32_e64 v93, v81, v85, s[30:31]
	v_cndmask_b32_e64 v94, v82, v86, s[30:31]
	v_cndmask_b32_e64 v95, v83, v87, s[30:31]
	v_cmp_gt_i32_e64 s[38:39], v24, v92
	v_cmp_gt_i32_e64 s[40:41], v24, v89
	v_cmp_gt_i32_e64 s[42:43], v24, v90
	v_cmp_gt_i32_e64 s[44:45], v24, v91
	v_addc_co_u32_e64 v136, s[36:37], 0, v136, s[38:39]
	v_addc_co_u32_e64 v137, s[36:37], 0, v137, s[40:41]
	v_addc_co_u32_e64 v138, s[36:37], 0, v138, s[42:43]
	v_addc_co_u32_e64 v139, s[36:37], 0, v139, s[44:45]
	v_cmp_gt_i32_e64 s[38:39], v25, v92
	v_cmp_gt_i32_e64 s[40:41], v25, v93
	v_cmp_gt_i32_e64 s[42:43], v25, v90
	v_cmp_gt_i32_e64 s[44:45], v25, v91
	v_addc_co_u32_e64 v136, s[36:37], 0, v136, s[38:39]
	v_addc_co_u32_e64 v137, s[36:37], 0, v137, s[40:41]
	v_addc_co_u32_e64 v138, s[36:37], 0, v138, s[42:43]
	v_addc_co_u32_e64 v139, s[36:37], 0, v139, s[44:45]
	v_cmp_gt_i32_e64 s[38:39], v26, v92
	v_cmp_gt_i32_e64 s[40:41], v26, v93
	v_cmp_gt_i32_e64 s[42:43], v26, v94
	v_cmp_gt_i32_e64 s[44:45], v26, v91
	v_addc_co_u32_e64 v136, s[36:37], 0, v136, s[38:39]
	v_addc_co_u32_e64 v137, s[36:37], 0, v137, s[40:41]
	v_addc_co_u32_e64 v138, s[36:37], 0, v138, s[42:43]
	v_addc_co_u32_e64 v139, s[36:37], 0, v139, s[44:45]
	v_cmp_gt_i32_e64 s[38:39], v27, v92
	v_cmp_gt_i32_e64 s[40:41], v27, v93
	v_cmp_gt_i32_e64 s[42:43], v27, v94
	v_cmp_gt_i32_e64 s[44:45], v27, v95
	v_addc_co_u32_e64 v136, s[36:37], 0, v136, s[38:39]
	v_addc_co_u32_e64 v137, s[36:37], 0, v137, s[40:41]
	v_addc_co_u32_e64 v138, s[36:37], 0, v138, s[42:43]
	v_addc_co_u32_e64 v139, s[36:37], 0, v139, s[44:45]
	s_waitcnt lgkmcnt(0)
	v_pk_add_f32 v[48:49], v[48:49], v[52:53]
	v_pk_add_f32 v[50:51], v[50:51], v[54:55]
	v_pk_add_f32 v[56:57], v[56:57], v[60:61]
	v_pk_add_f32 v[58:59], v[58:59], v[62:63]
	v_pk_add_f32 v[28:29], v[48:49], v[56:57]
	v_pk_add_f32 v[30:31], v[50:51], v[58:59]
	s_cmp_gt_i32 s18, 27
	s_cselect_b64 s[28:29], -1, 0
	v_cndmask_b32_e64 v28, -1, v28, s[28:29]
	s_cmp_gt_i32 s18, 28
	s_cselect_b64 s[28:29], -1, 0
	v_cndmask_b32_e64 v29, -1, v29, s[28:29]
	v_cmp_gt_i32_e64 s[38:39], v28, v80
	v_cmp_gt_i32_e64 s[40:41], v28, v93
	v_cmp_gt_i32_e64 s[42:43], v28, v94
	v_cmp_gt_i32_e64 s[44:45], v28, v95
	v_addc_co_u32_e64 v136, s[36:37], 0, v136, s[38:39]
	v_addc_co_u32_e64 v137, s[36:37], 0, v137, s[40:41]
	v_addc_co_u32_e64 v138, s[36:37], 0, v138, s[42:43]
	v_addc_co_u32_e64 v139, s[36:37], 0, v139, s[44:45]
	v_cmp_gt_i32_e64 s[38:39], v29, v80
	v_cmp_gt_i32_e64 s[40:41], v29, v81
	v_cmp_gt_i32_e64 s[42:43], v29, v94
	v_cmp_gt_i32_e64 s[44:45], v29, v95
	v_addc_co_u32_e64 v136, s[36:37], 0, v136, s[38:39]
	v_addc_co_u32_e64 v137, s[36:37], 0, v137, s[40:41]
	v_addc_co_u32_e64 v138, s[36:37], 0, v138, s[42:43]
	v_addc_co_u32_e64 v139, s[36:37], 0, v139, s[44:45]
	v_cmp_gt_i32_e64 s[38:39], s17, v136
	v_cmp_gt_i32_e64 s[40:41], s17, v137
	v_cmp_gt_i32_e64 s[42:43], s17, v138
	v_cmp_gt_i32_e64 s[44:45], s17, v139
	s_and_b64 s[38:39], s[38:39], s[20:21]
	s_and_b64 s[40:41], s[40:41], s[22:23]
	s_and_b64 s[42:43], s[42:43], s[24:25]
	s_and_b64 s[44:45], s[44:45], s[26:27]
	v_cndmask_b32_e64 v140, 0, v231, s[38:39]
	v_cndmask_b32_e64 v141, 0, v232, s[40:41]
	v_cndmask_b32_e64 v142, 0, v234, s[42:43]
	v_cndmask_b32_e64 v143, 0, v236, s[44:45]
	v_or3_b32 v140, v140, v141, v142
	v_or_b32_e32 v140, v140, v143
	s_nop 1
	v_or_b32_dpp v141, v140, v140 quad_perm:[1,0,3,2] row_mask:0xf bank_mask:0xf
	s_nop 1
	v_or_b32_dpp v140, v141, v141 quad_perm:[2,3,0,1] row_mask:0xf bank_mask:0xf
	s_nop 1
	v_or_b32_dpp v141, v140, v140 row_half_mirror row_mask:0xf bank_mask:0xf
	v_cmp_eq_u32_e32 vcc, 0, v177
	v_or_b32_e32 v141, s16, v141
	s_and_saveexec_b64 s[0:1], vcc
	s_cbranch_execz .LBB0_398
	ds_write_b32 v179, v141
